# scanner v2: 2 accumulator chains per mat-vec, B operand via row-masked DPP add (hazard slots filled with deferred-y FMAs), y finished per pair of steps with one 64-lane store
# speedup vs baseline: 1.1542x; 1.0067x over previous
; __device__ void scan_chain(PRef p, int l, int chain, ScanSm* sm) {
;     ...
;   if (wave < 2) {
;     const int kh = wave;
;     float S[32];
; #pragma unroll
;     for (int j = 0; j < 32; j++) S[j] = 0.f;
;     bf16* Y = p.HY + (size_t)d * NROWS * 512 + h * 64 + lane;
;     float yprev = 0.f;
;     int rowcur = b * TPB + (d ? 255 : 0), rowprev = rowcur;
;     const int rstep = d ? -1 : 1;
;     const int ko = 32 * kh + (lane & 15);
.LBB0_606:
	s_andn2_saveexec_b64 s[6:7], s[20:21]
	s_cbranch_execz .LBB0_564
	v_and_b32_e32 v0, 63, v196
	v_lshrrev_b32_e32 v1, 6, v196
	v_and_b32_e32 v2, 12, v0
	v_lshlrev_b32_e32 v2, 3, v2
	v_lshrrev_b32_e32 v4, 5, v0
	v_lshl_add_u32 v2, v4, 4, v2
	v_and_b32_e32 v5, 3, v0
	v_lshl_add_u32 v10, v5, 2, v2
	v_and_b32_e32 v6, 31, v0
	v_lshlrev_b32_e32 v7, 2, v6
	v_lshlrev_b32_e32 v8, 8, v4
	v_sub_u32_e32 v11, v7, v8
	v_add_u32_e32 v11, 0x300, v11
	v_lshl_add_u32 v12, v1, 7, v7
	v_add_u32_e32 v12, 0x500, v12
	v_lshl_add_u32 v13, v1, 5, v6
	s_lshl_b32 s0, s63, 6
	v_add_u32_e32 v13, s0, v13
	v_lshlrev_b32_e32 v13, 1, v13
	v_lshlrev_b32_e32 v9, 10, v4
	v_sub_u32_e32 v2, 0x400, v9
	s_cmp_eq_u32 s62, 0
	s_cselect_b64 vcc, -1, 0
	s_nop 1
	v_cndmask_b32_e32 v9, v2, v9, vcc
	v_add_u32_e32 v13, v13, v9
	s_mul_i32 s0, s62, 0x2400000
	s_add_u32 s12, s86, s0
	s_addc_u32 s13, s87, 0
	s_cmp_eq_u32 s62, 0
	s_mov_b32 s20, 0xfffff800
	s_cselect_b32 s20, 0x800, s20
	s_cselect_b32 s21, 0, -1
	s_cselect_b32 s0, 0, 0xfe
	s_add_i32 s0, s28, s0
	s_lshl_b32 s0, s0, 10
	s_add_u32 s16, s12, s0
	s_addc_u32 s17, s13, 0
	v_mov_b32_e32 v32, 0
	v_mov_b32_e32 v33, 0
	v_mov_b32_e32 v34, 0
	v_mov_b32_e32 v35, 0
	v_mov_b32_e32 v36, 0
	v_mov_b32_e32 v37, 0
	v_mov_b32_e32 v38, 0
	v_mov_b32_e32 v39, 0
	v_mov_b32_e32 v40, 0
	v_mov_b32_e32 v41, 0
	v_mov_b32_e32 v42, 0
	v_mov_b32_e32 v43, 0
	v_mov_b32_e32 v44, 0
	v_mov_b32_e32 v45, 0
	v_mov_b32_e32 v46, 0
	v_mov_b32_e32 v47, 0
	v_mov_b32_e32 v48, 0
	v_mov_b32_e32 v49, 0
	v_mov_b32_e32 v50, 0
	v_mov_b32_e32 v51, 0
	v_mov_b32_e32 v52, 0
	v_mov_b32_e32 v53, 0
	v_mov_b32_e32 v54, 0
	v_mov_b32_e32 v55, 0
	v_mov_b32_e32 v56, 0
	v_mov_b32_e32 v57, 0
	v_mov_b32_e32 v58, 0
	v_mov_b32_e32 v59, 0
	v_mov_b32_e32 v60, 0
	v_mov_b32_e32 v61, 0
	v_mov_b32_e32 v62, 0
	v_mov_b32_e32 v63, 0
	s_mov_b32 s15, 0
.Lscan_chunk:
	s_and_b32 s22, s15, 1
	s_mulk_i32 s22, 0x6000
	v_add_u32_e32 v14, s22, v10
	v_add_u32_e32 v15, s22, v11
	v_add_u32_e32 v16, s22, v12
	s_cmp_lg_u32 s15, 16
	s_cbranch_scc1 .Lscan_rowok
	s_cmp_eq_u32 s62, 0
	s_cselect_b32 s0, 0, 0x7fe
	s_add_i32 s0, s28, s0
	s_addk_i32 s0, 0x100
	s_lshl_b32 s0, s0, 10
	s_add_u32 s16, s12, s0
	s_addc_u32 s17, s13, 0
.Lscan_rowok:
	s_waitcnt lgkmcnt(0)
	s_barrier
	ds_read_b32 v100, v14 offset:256
	ds_read_b32 v101, v14 offset:384
	ds_read_b32 v104, v15 offset:0
	ds_read_b32 v105, v15 offset:128
	ds_read_b32 v108, v16 offset:0
	ds_read_b32 v110, v14 offset:1024
	ds_read_b32 v111, v14 offset:1152
	s_waitcnt lgkmcnt(0)
	ds_read_b32 v102, v14 offset:1792
	ds_read_b32 v103, v14 offset:1920
	ds_read_b32 v106, v15 offset:1536
	ds_read_b32 v107, v15 offset:1664
	ds_read_b32 v109, v16 offset:1536
	ds_read_b32 v112, v14 offset:2560
	ds_read_b32 v113, v14 offset:2688
	v_mul_f32_dpp v120, v100, v32 row_newbcast:0 row_mask:0xf bank_mask:0xf
	v_mul_f32_dpp v121, v100, v33 row_newbcast:1 row_mask:0xf bank_mask:0xf
	v_fmac_f32_dpp v120, v100, v34 row_newbcast:2 row_mask:0xf bank_mask:0xf
	v_fmac_f32_dpp v121, v100, v35 row_newbcast:3 row_mask:0xf bank_mask:0xf
	v_fmac_f32_dpp v120, v100, v36 row_newbcast:4 row_mask:0xf bank_mask:0xf
	v_fmac_f32_dpp v121, v100, v37 row_newbcast:5 row_mask:0xf bank_mask:0xf
	v_fmac_f32_dpp v120, v100, v38 row_newbcast:6 row_mask:0xf bank_mask:0xf
	v_fmac_f32_dpp v121, v100, v39 row_newbcast:7 row_mask:0xf bank_mask:0xf
	v_fmac_f32_dpp v120, v100, v40 row_newbcast:8 row_mask:0xf bank_mask:0xf
	v_fmac_f32_dpp v121, v100, v41 row_newbcast:9 row_mask:0xf bank_mask:0xf
	v_fmac_f32_dpp v120, v100, v42 row_newbcast:10 row_mask:0xf bank_mask:0xf
	v_fmac_f32_dpp v121, v100, v43 row_newbcast:11 row_mask:0xf bank_mask:0xf
	v_fmac_f32_dpp v120, v100, v44 row_newbcast:12 row_mask:0xf bank_mask:0xf
	v_fmac_f32_dpp v121, v100, v45 row_newbcast:13 row_mask:0xf bank_mask:0xf
	v_fmac_f32_dpp v120, v100, v46 row_newbcast:14 row_mask:0xf bank_mask:0xf
	v_fmac_f32_dpp v121, v100, v47 row_newbcast:15 row_mask:0xf bank_mask:0xf
	v_fmac_f32_dpp v120, v101, v48 row_newbcast:0 row_mask:0xf bank_mask:0xf
	v_fmac_f32_dpp v121, v101, v49 row_newbcast:1 row_mask:0xf bank_mask:0xf
	v_fmac_f32_dpp v120, v101, v50 row_newbcast:2 row_mask:0xf bank_mask:0xf
	v_fmac_f32_dpp v121, v101, v51 row_newbcast:3 row_mask:0xf bank_mask:0xf
	v_fmac_f32_dpp v120, v101, v52 row_newbcast:4 row_mask:0xf bank_mask:0xf
	v_fmac_f32_dpp v121, v101, v53 row_newbcast:5 row_mask:0xf bank_mask:0xf
	v_fmac_f32_dpp v120, v101, v54 row_newbcast:6 row_mask:0xf bank_mask:0xf
	v_fmac_f32_dpp v121, v101, v55 row_newbcast:7 row_mask:0xf bank_mask:0xf
	v_fmac_f32_dpp v120, v101, v56 row_newbcast:8 row_mask:0xf bank_mask:0xf
	v_fmac_f32_dpp v121, v101, v57 row_newbcast:9 row_mask:0xf bank_mask:0xf
	v_fmac_f32_dpp v120, v101, v58 row_newbcast:10 row_mask:0xf bank_mask:0xf
	v_fmac_f32_dpp v121, v101, v59 row_newbcast:11 row_mask:0xf bank_mask:0xf
	v_fmac_f32_dpp v120, v101, v60 row_newbcast:12 row_mask:0xf bank_mask:0xf
	v_fmac_f32_dpp v121, v101, v61 row_newbcast:13 row_mask:0xf bank_mask:0xf
	v_fmac_f32_dpp v120, v101, v62 row_newbcast:14 row_mask:0xf bank_mask:0xf
	v_fmac_f32_dpp v121, v101, v63 row_newbcast:15 row_mask:0xf bank_mask:0xf
	v_add_f32_e32 v128, v120, v121
	s_nop 1
	v_permlane32_swap_b32 v129, v128
	s_nop 1
	v_add_f32_dpp v108, -v129, -v128 quad_perm:[0,1,2,3] row_mask:0xc bank_mask:0xf
	s_nop 1
	v_mfma_f32_32x32x2_f32 v[64:79], v104, v108, v[32:47]
	s_nop 15
	v_mfma_f32_32x32x2_f32 v[80:95], v105, v108, v[48:63]
	s_nop 7
	s_waitcnt lgkmcnt(0)
	ds_read_b32 v100, v14 offset:3328
	ds_read_b32 v101, v14 offset:3456
	ds_read_b32 v104, v15 offset:3072
	ds_read_b32 v105, v15 offset:3200
	ds_read_b32 v108, v16 offset:3072
	ds_read_b32 v114, v14 offset:4096
	ds_read_b32 v115, v14 offset:4224
	v_mul_f32_dpp v120, v102, v64 row_newbcast:0 row_mask:0xf bank_mask:0xf
	v_mul_f32_dpp v121, v102, v65 row_newbcast:1 row_mask:0xf bank_mask:0xf
	v_fmac_f32_dpp v120, v102, v66 row_newbcast:2 row_mask:0xf bank_mask:0xf
	v_fmac_f32_dpp v121, v102, v67 row_newbcast:3 row_mask:0xf bank_mask:0xf
	v_fmac_f32_dpp v120, v102, v68 row_newbcast:4 row_mask:0xf bank_mask:0xf
	v_fmac_f32_dpp v121, v102, v69 row_newbcast:5 row_mask:0xf bank_mask:0xf
	v_fmac_f32_dpp v120, v102, v70 row_newbcast:6 row_mask:0xf bank_mask:0xf
	v_fmac_f32_dpp v121, v102, v71 row_newbcast:7 row_mask:0xf bank_mask:0xf
	v_fmac_f32_dpp v120, v102, v72 row_newbcast:8 row_mask:0xf bank_mask:0xf
	v_fmac_f32_dpp v121, v102, v73 row_newbcast:9 row_mask:0xf bank_mask:0xf
	v_fmac_f32_dpp v120, v102, v74 row_newbcast:10 row_mask:0xf bank_mask:0xf
	v_fmac_f32_dpp v121, v102, v75 row_newbcast:11 row_mask:0xf bank_mask:0xf
	v_fmac_f32_dpp v120, v102, v76 row_newbcast:12 row_mask:0xf bank_mask:0xf
	v_fmac_f32_dpp v121, v102, v77 row_newbcast:13 row_mask:0xf bank_mask:0xf
	v_fmac_f32_dpp v120, v102, v78 row_newbcast:14 row_mask:0xf bank_mask:0xf
	v_fmac_f32_dpp v121, v102, v79 row_newbcast:15 row_mask:0xf bank_mask:0xf
	v_fmac_f32_dpp v120, v103, v80 row_newbcast:0 row_mask:0xf bank_mask:0xf
	v_fmac_f32_dpp v121, v103, v81 row_newbcast:1 row_mask:0xf bank_mask:0xf
	v_fmac_f32_dpp v120, v103, v82 row_newbcast:2 row_mask:0xf bank_mask:0xf
	v_fmac_f32_dpp v121, v103, v83 row_newbcast:3 row_mask:0xf bank_mask:0xf
	v_fmac_f32_dpp v120, v103, v84 row_newbcast:4 row_mask:0xf bank_mask:0xf
	v_fmac_f32_dpp v121, v103, v85 row_newbcast:5 row_mask:0xf bank_mask:0xf
	v_fmac_f32_dpp v120, v103, v86 row_newbcast:6 row_mask:0xf bank_mask:0xf
	v_fmac_f32_dpp v121, v103, v87 row_newbcast:7 row_mask:0xf bank_mask:0xf
	v_fmac_f32_dpp v120, v103, v88 row_newbcast:8 row_mask:0xf bank_mask:0xf
	v_fmac_f32_dpp v121, v103, v89 row_newbcast:9 row_mask:0xf bank_mask:0xf
	v_fmac_f32_dpp v120, v103, v90 row_newbcast:10 row_mask:0xf bank_mask:0xf
	v_fmac_f32_dpp v121, v103, v91 row_newbcast:11 row_mask:0xf bank_mask:0xf
	v_fmac_f32_dpp v120, v103, v92 row_newbcast:12 row_mask:0xf bank_mask:0xf
	v_fmac_f32_dpp v121, v103, v93 row_newbcast:13 row_mask:0xf bank_mask:0xf
	v_fmac_f32_dpp v120, v103, v94 row_newbcast:14 row_mask:0xf bank_mask:0xf
	v_fmac_f32_dpp v121, v103, v95 row_newbcast:15 row_mask:0xf bank_mask:0xf
	v_add_f32_e32 v128, v120, v121
	v_mul_f32_dpp v124, v110, v64 row_newbcast:0 row_mask:0xf bank_mask:0xf
	v_mul_f32_dpp v125, v110, v65 row_newbcast:1 row_mask:0xf bank_mask:0xf
	v_permlane32_swap_b32 v129, v128
	v_fmac_f32_dpp v124, v110, v66 row_newbcast:2 row_mask:0xf bank_mask:0xf
	v_fmac_f32_dpp v125, v110, v67 row_newbcast:3 row_mask:0xf bank_mask:0xf
	v_add_f32_dpp v109, -v129, -v128 quad_perm:[0,1,2,3] row_mask:0xc bank_mask:0xf
	v_fmac_f32_dpp v124, v110, v68 row_newbcast:4 row_mask:0xf bank_mask:0xf
	v_fmac_f32_dpp v125, v110, v69 row_newbcast:5 row_mask:0xf bank_mask:0xf
	v_mfma_f32_32x32x2_f32 v[32:47], v106, v109, v[64:79]
	v_fmac_f32_dpp v124, v110, v70 row_newbcast:6 row_mask:0xf bank_mask:0xf
	v_fmac_f32_dpp v125, v110, v71 row_newbcast:7 row_mask:0xf bank_mask:0xf
	v_fmac_f32_dpp v124, v110, v72 row_newbcast:8 row_mask:0xf bank_mask:0xf
	v_fmac_f32_dpp v125, v110, v73 row_newbcast:9 row_mask:0xf bank_mask:0xf
	v_fmac_f32_dpp v124, v110, v74 row_newbcast:10 row_mask:0xf bank_mask:0xf
	v_fmac_f32_dpp v125, v110, v75 row_newbcast:11 row_mask:0xf bank_mask:0xf
	v_fmac_f32_dpp v124, v110, v76 row_newbcast:12 row_mask:0xf bank_mask:0xf
	v_fmac_f32_dpp v125, v110, v77 row_newbcast:13 row_mask:0xf bank_mask:0xf
	v_fmac_f32_dpp v124, v110, v78 row_newbcast:14 row_mask:0xf bank_mask:0xf
	v_fmac_f32_dpp v125, v110, v79 row_newbcast:15 row_mask:0xf bank_mask:0xf
	v_fmac_f32_dpp v124, v111, v80 row_newbcast:0 row_mask:0xf bank_mask:0xf
	v_fmac_f32_dpp v125, v111, v81 row_newbcast:1 row_mask:0xf bank_mask:0xf
	v_fmac_f32_dpp v124, v111, v82 row_newbcast:2 row_mask:0xf bank_mask:0xf
	v_fmac_f32_dpp v125, v111, v83 row_newbcast:3 row_mask:0xf bank_mask:0xf
	v_mfma_f32_32x32x2_f32 v[48:63], v107, v109, v[80:95]
	v_fmac_f32_dpp v124, v111, v84 row_newbcast:4 row_mask:0xf bank_mask:0xf
	v_fmac_f32_dpp v125, v111, v85 row_newbcast:5 row_mask:0xf bank_mask:0xf
	v_fmac_f32_dpp v124, v111, v86 row_newbcast:6 row_mask:0xf bank_mask:0xf
	v_fmac_f32_dpp v125, v111, v87 row_newbcast:7 row_mask:0xf bank_mask:0xf
	v_fmac_f32_dpp v124, v111, v88 row_newbcast:8 row_mask:0xf bank_mask:0xf
	v_fmac_f32_dpp v125, v111, v89 row_newbcast:9 row_mask:0xf bank_mask:0xf
	v_fmac_f32_dpp v124, v111, v90 row_newbcast:10 row_mask:0xf bank_mask:0xf
	v_fmac_f32_dpp v125, v111, v91 row_newbcast:11 row_mask:0xf bank_mask:0xf
	v_fmac_f32_dpp v124, v111, v92 row_newbcast:12 row_mask:0xf bank_mask:0xf
	v_fmac_f32_dpp v125, v111, v93 row_newbcast:13 row_mask:0xf bank_mask:0xf
	v_fmac_f32_dpp v124, v111, v94 row_newbcast:14 row_mask:0xf bank_mask:0xf
	v_fmac_f32_dpp v125, v111, v95 row_newbcast:15 row_mask:0xf bank_mask:0xf
	v_add_f32_e32 v130, v124, v125
	s_waitcnt lgkmcnt(0)
	ds_read_b32 v102, v14 offset:4864
	ds_read_b32 v103, v14 offset:4992
	ds_read_b32 v106, v15 offset:4608
	ds_read_b32 v107, v15 offset:4736
	ds_read_b32 v109, v16 offset:4608
	ds_read_b32 v116, v14 offset:5632
	ds_read_b32 v117, v14 offset:5760
	v_mul_f32_dpp v120, v100, v32 row_newbcast:0 row_mask:0xf bank_mask:0xf
	v_mul_f32_dpp v121, v100, v33 row_newbcast:1 row_mask:0xf bank_mask:0xf
	v_fmac_f32_dpp v120, v100, v34 row_newbcast:2 row_mask:0xf bank_mask:0xf
	v_fmac_f32_dpp v121, v100, v35 row_newbcast:3 row_mask:0xf bank_mask:0xf
	v_fmac_f32_dpp v120, v100, v36 row_newbcast:4 row_mask:0xf bank_mask:0xf
	v_fmac_f32_dpp v121, v100, v37 row_newbcast:5 row_mask:0xf bank_mask:0xf
	v_fmac_f32_dpp v120, v100, v38 row_newbcast:6 row_mask:0xf bank_mask:0xf
	v_fmac_f32_dpp v121, v100, v39 row_newbcast:7 row_mask:0xf bank_mask:0xf
	v_fmac_f32_dpp v120, v100, v40 row_newbcast:8 row_mask:0xf bank_mask:0xf
	v_fmac_f32_dpp v121, v100, v41 row_newbcast:9 row_mask:0xf bank_mask:0xf
	v_fmac_f32_dpp v120, v100, v42 row_newbcast:10 row_mask:0xf bank_mask:0xf
	v_fmac_f32_dpp v121, v100, v43 row_newbcast:11 row_mask:0xf bank_mask:0xf
	v_fmac_f32_dpp v120, v100, v44 row_newbcast:12 row_mask:0xf bank_mask:0xf
	v_fmac_f32_dpp v121, v100, v45 row_newbcast:13 row_mask:0xf bank_mask:0xf
	v_fmac_f32_dpp v120, v100, v46 row_newbcast:14 row_mask:0xf bank_mask:0xf
	v_fmac_f32_dpp v121, v100, v47 row_newbcast:15 row_mask:0xf bank_mask:0xf
	v_fmac_f32_dpp v120, v101, v48 row_newbcast:0 row_mask:0xf bank_mask:0xf
	v_fmac_f32_dpp v121, v101, v49 row_newbcast:1 row_mask:0xf bank_mask:0xf
	v_fmac_f32_dpp v120, v101, v50 row_newbcast:2 row_mask:0xf bank_mask:0xf
	v_fmac_f32_dpp v121, v101, v51 row_newbcast:3 row_mask:0xf bank_mask:0xf
	v_fmac_f32_dpp v120, v101, v52 row_newbcast:4 row_mask:0xf bank_mask:0xf
	v_fmac_f32_dpp v121, v101, v53 row_newbcast:5 row_mask:0xf bank_mask:0xf
	v_fmac_f32_dpp v120, v101, v54 row_newbcast:6 row_mask:0xf bank_mask:0xf
	v_fmac_f32_dpp v121, v101, v55 row_newbcast:7 row_mask:0xf bank_mask:0xf
	v_fmac_f32_dpp v120, v101, v56 row_newbcast:8 row_mask:0xf bank_mask:0xf
	v_fmac_f32_dpp v121, v101, v57 row_newbcast:9 row_mask:0xf bank_mask:0xf
	v_fmac_f32_dpp v120, v101, v58 row_newbcast:10 row_mask:0xf bank_mask:0xf
	v_fmac_f32_dpp v121, v101, v59 row_newbcast:11 row_mask:0xf bank_mask:0xf
	v_fmac_f32_dpp v120, v101, v60 row_newbcast:12 row_mask:0xf bank_mask:0xf
	v_fmac_f32_dpp v121, v101, v61 row_newbcast:13 row_mask:0xf bank_mask:0xf
	v_fmac_f32_dpp v120, v101, v62 row_newbcast:14 row_mask:0xf bank_mask:0xf
	v_fmac_f32_dpp v121, v101, v63 row_newbcast:15 row_mask:0xf bank_mask:0xf
	v_add_f32_e32 v128, v120, v121
	v_mul_f32_dpp v124, v112, v32 row_newbcast:0 row_mask:0xf bank_mask:0xf
	v_mul_f32_dpp v125, v112, v33 row_newbcast:1 row_mask:0xf bank_mask:0xf
	v_permlane32_swap_b32 v129, v128
	v_fmac_f32_dpp v124, v112, v34 row_newbcast:2 row_mask:0xf bank_mask:0xf
	v_fmac_f32_dpp v125, v112, v35 row_newbcast:3 row_mask:0xf bank_mask:0xf
	v_add_f32_dpp v108, -v129, -v128 quad_perm:[0,1,2,3] row_mask:0xc bank_mask:0xf
	v_fmac_f32_dpp v124, v112, v36 row_newbcast:4 row_mask:0xf bank_mask:0xf
	v_fmac_f32_dpp v125, v112, v37 row_newbcast:5 row_mask:0xf bank_mask:0xf
	v_mfma_f32_32x32x2_f32 v[64:79], v104, v108, v[32:47]
	v_fmac_f32_dpp v124, v112, v38 row_newbcast:6 row_mask:0xf bank_mask:0xf
	v_fmac_f32_dpp v125, v112, v39 row_newbcast:7 row_mask:0xf bank_mask:0xf
	v_fmac_f32_dpp v124, v112, v40 row_newbcast:8 row_mask:0xf bank_mask:0xf
	v_fmac_f32_dpp v125, v112, v41 row_newbcast:9 row_mask:0xf bank_mask:0xf
	v_fmac_f32_dpp v124, v112, v42 row_newbcast:10 row_mask:0xf bank_mask:0xf
	v_fmac_f32_dpp v125, v112, v43 row_newbcast:11 row_mask:0xf bank_mask:0xf
	v_fmac_f32_dpp v124, v112, v44 row_newbcast:12 row_mask:0xf bank_mask:0xf
	v_fmac_f32_dpp v125, v112, v45 row_newbcast:13 row_mask:0xf bank_mask:0xf
	v_fmac_f32_dpp v124, v112, v46 row_newbcast:14 row_mask:0xf bank_mask:0xf
	v_fmac_f32_dpp v125, v112, v47 row_newbcast:15 row_mask:0xf bank_mask:0xf
	v_fmac_f32_dpp v124, v113, v48 row_newbcast:0 row_mask:0xf bank_mask:0xf
	v_fmac_f32_dpp v125, v113, v49 row_newbcast:1 row_mask:0xf bank_mask:0xf
	v_fmac_f32_dpp v124, v113, v50 row_newbcast:2 row_mask:0xf bank_mask:0xf
	v_fmac_f32_dpp v125, v113, v51 row_newbcast:3 row_mask:0xf bank_mask:0xf
	v_mfma_f32_32x32x2_f32 v[80:95], v105, v108, v[48:63]
	v_fmac_f32_dpp v124, v113, v52 row_newbcast:4 row_mask:0xf bank_mask:0xf
	v_fmac_f32_dpp v125, v113, v53 row_newbcast:5 row_mask:0xf bank_mask:0xf
	v_fmac_f32_dpp v124, v113, v54 row_newbcast:6 row_mask:0xf bank_mask:0xf
	v_fmac_f32_dpp v125, v113, v55 row_newbcast:7 row_mask:0xf bank_mask:0xf
	v_fmac_f32_dpp v124, v113, v56 row_newbcast:8 row_mask:0xf bank_mask:0xf
	v_fmac_f32_dpp v125, v113, v57 row_newbcast:9 row_mask:0xf bank_mask:0xf
	v_fmac_f32_dpp v124, v113, v58 row_newbcast:10 row_mask:0xf bank_mask:0xf
	v_fmac_f32_dpp v125, v113, v59 row_newbcast:11 row_mask:0xf bank_mask:0xf
	v_fmac_f32_dpp v124, v113, v60 row_newbcast:12 row_mask:0xf bank_mask:0xf
	v_fmac_f32_dpp v125, v113, v61 row_newbcast:13 row_mask:0xf bank_mask:0xf
	v_fmac_f32_dpp v124, v113, v62 row_newbcast:14 row_mask:0xf bank_mask:0xf
	v_fmac_f32_dpp v125, v113, v63 row_newbcast:15 row_mask:0xf bank_mask:0xf
	v_add_f32_e32 v131, v124, v125
	s_nop 1
	v_permlane32_swap_b32 v130, v131
	v_add_f32_e32 v133, v130, v131
	v_cvt_pk_bf16_f32 v133, v133, v133
	global_store_short v13, v133, s[16:17]
	s_add_u32 s16, s16, s20
	s_addc_u32 s17, s17, s21
	s_waitcnt lgkmcnt(0)
	ds_read_b32 v100, v14 offset:6400
	ds_read_b32 v101, v14 offset:6528
	ds_read_b32 v104, v15 offset:6144
	ds_read_b32 v105, v15 offset:6272
	ds_read_b32 v108, v16 offset:6144
	ds_read_b32 v110, v14 offset:7168
	ds_read_b32 v111, v14 offset:7296
	v_mul_f32_dpp v120, v102, v64 row_newbcast:0 row_mask:0xf bank_mask:0xf
	v_mul_f32_dpp v121, v102, v65 row_newbcast:1 row_mask:0xf bank_mask:0xf
	v_fmac_f32_dpp v120, v102, v66 row_newbcast:2 row_mask:0xf bank_mask:0xf
	v_fmac_f32_dpp v121, v102, v67 row_newbcast:3 row_mask:0xf bank_mask:0xf
	v_fmac_f32_dpp v120, v102, v68 row_newbcast:4 row_mask:0xf bank_mask:0xf
	v_fmac_f32_dpp v121, v102, v69 row_newbcast:5 row_mask:0xf bank_mask:0xf
	v_fmac_f32_dpp v120, v102, v70 row_newbcast:6 row_mask:0xf bank_mask:0xf
	v_fmac_f32_dpp v121, v102, v71 row_newbcast:7 row_mask:0xf bank_mask:0xf
	v_fmac_f32_dpp v120, v102, v72 row_newbcast:8 row_mask:0xf bank_mask:0xf
	v_fmac_f32_dpp v121, v102, v73 row_newbcast:9 row_mask:0xf bank_mask:0xf
	v_fmac_f32_dpp v120, v102, v74 row_newbcast:10 row_mask:0xf bank_mask:0xf
	v_fmac_f32_dpp v121, v102, v75 row_newbcast:11 row_mask:0xf bank_mask:0xf
	v_fmac_f32_dpp v120, v102, v76 row_newbcast:12 row_mask:0xf bank_mask:0xf
	v_fmac_f32_dpp v121, v102, v77 row_newbcast:13 row_mask:0xf bank_mask:0xf
	v_fmac_f32_dpp v120, v102, v78 row_newbcast:14 row_mask:0xf bank_mask:0xf
	v_fmac_f32_dpp v121, v102, v79 row_newbcast:15 row_mask:0xf bank_mask:0xf
	v_fmac_f32_dpp v120, v103, v80 row_newbcast:0 row_mask:0xf bank_mask:0xf
	v_fmac_f32_dpp v121, v103, v81 row_newbcast:1 row_mask:0xf bank_mask:0xf
	v_fmac_f32_dpp v120, v103, v82 row_newbcast:2 row_mask:0xf bank_mask:0xf
	v_fmac_f32_dpp v121, v103, v83 row_newbcast:3 row_mask:0xf bank_mask:0xf
	v_fmac_f32_dpp v120, v103, v84 row_newbcast:4 row_mask:0xf bank_mask:0xf
	v_fmac_f32_dpp v121, v103, v85 row_newbcast:5 row_mask:0xf bank_mask:0xf
	v_fmac_f32_dpp v120, v103, v86 row_newbcast:6 row_mask:0xf bank_mask:0xf
	v_fmac_f32_dpp v121, v103, v87 row_newbcast:7 row_mask:0xf bank_mask:0xf
	v_fmac_f32_dpp v120, v103, v88 row_newbcast:8 row_mask:0xf bank_mask:0xf
	v_fmac_f32_dpp v121, v103, v89 row_newbcast:9 row_mask:0xf bank_mask:0xf
	v_fmac_f32_dpp v120, v103, v90 row_newbcast:10 row_mask:0xf bank_mask:0xf
	v_fmac_f32_dpp v121, v103, v91 row_newbcast:11 row_mask:0xf bank_mask:0xf
	v_fmac_f32_dpp v120, v103, v92 row_newbcast:12 row_mask:0xf bank_mask:0xf
	v_fmac_f32_dpp v121, v103, v93 row_newbcast:13 row_mask:0xf bank_mask:0xf
	v_fmac_f32_dpp v120, v103, v94 row_newbcast:14 row_mask:0xf bank_mask:0xf
	v_fmac_f32_dpp v121, v103, v95 row_newbcast:15 row_mask:0xf bank_mask:0xf
	v_add_f32_e32 v128, v120, v121
	v_mul_f32_dpp v124, v114, v64 row_newbcast:0 row_mask:0xf bank_mask:0xf
	v_mul_f32_dpp v125, v114, v65 row_newbcast:1 row_mask:0xf bank_mask:0xf
	v_permlane32_swap_b32 v129, v128
	v_fmac_f32_dpp v124, v114, v66 row_newbcast:2 row_mask:0xf bank_mask:0xf
	v_fmac_f32_dpp v125, v114, v67 row_newbcast:3 row_mask:0xf bank_mask:0xf
	v_add_f32_dpp v109, -v129, -v128 quad_perm:[0,1,2,3] row_mask:0xc bank_mask:0xf
	v_fmac_f32_dpp v124, v114, v68 row_newbcast:4 row_mask:0xf bank_mask:0xf
	v_fmac_f32_dpp v125, v114, v69 row_newbcast:5 row_mask:0xf bank_mask:0xf
	v_mfma_f32_32x32x2_f32 v[32:47], v106, v109, v[64:79]
	v_fmac_f32_dpp v124, v114, v70 row_newbcast:6 row_mask:0xf bank_mask:0xf
	v_fmac_f32_dpp v125, v114, v71 row_newbcast:7 row_mask:0xf bank_mask:0xf
	v_fmac_f32_dpp v124, v114, v72 row_newbcast:8 row_mask:0xf bank_mask:0xf
	v_fmac_f32_dpp v125, v114, v73 row_newbcast:9 row_mask:0xf bank_mask:0xf
	v_fmac_f32_dpp v124, v114, v74 row_newbcast:10 row_mask:0xf bank_mask:0xf
	v_fmac_f32_dpp v125, v114, v75 row_newbcast:11 row_mask:0xf bank_mask:0xf
	v_fmac_f32_dpp v124, v114, v76 row_newbcast:12 row_mask:0xf bank_mask:0xf
	v_fmac_f32_dpp v125, v114, v77 row_newbcast:13 row_mask:0xf bank_mask:0xf
	v_fmac_f32_dpp v124, v114, v78 row_newbcast:14 row_mask:0xf bank_mask:0xf
	v_fmac_f32_dpp v125, v114, v79 row_newbcast:15 row_mask:0xf bank_mask:0xf
	v_fmac_f32_dpp v124, v115, v80 row_newbcast:0 row_mask:0xf bank_mask:0xf
	v_fmac_f32_dpp v125, v115, v81 row_newbcast:1 row_mask:0xf bank_mask:0xf
	v_fmac_f32_dpp v124, v115, v82 row_newbcast:2 row_mask:0xf bank_mask:0xf
	v_fmac_f32_dpp v125, v115, v83 row_newbcast:3 row_mask:0xf bank_mask:0xf
	v_mfma_f32_32x32x2_f32 v[48:63], v107, v109, v[80:95]
	v_fmac_f32_dpp v124, v115, v84 row_newbcast:4 row_mask:0xf bank_mask:0xf
	v_fmac_f32_dpp v125, v115, v85 row_newbcast:5 row_mask:0xf bank_mask:0xf
	v_fmac_f32_dpp v124, v115, v86 row_newbcast:6 row_mask:0xf bank_mask:0xf
	v_fmac_f32_dpp v125, v115, v87 row_newbcast:7 row_mask:0xf bank_mask:0xf
	v_fmac_f32_dpp v124, v115, v88 row_newbcast:8 row_mask:0xf bank_mask:0xf
	v_fmac_f32_dpp v125, v115, v89 row_newbcast:9 row_mask:0xf bank_mask:0xf
	v_fmac_f32_dpp v124, v115, v90 row_newbcast:10 row_mask:0xf bank_mask:0xf
	v_fmac_f32_dpp v125, v115, v91 row_newbcast:11 row_mask:0xf bank_mask:0xf
	v_fmac_f32_dpp v124, v115, v92 row_newbcast:12 row_mask:0xf bank_mask:0xf
	v_fmac_f32_dpp v125, v115, v93 row_newbcast:13 row_mask:0xf bank_mask:0xf
	v_fmac_f32_dpp v124, v115, v94 row_newbcast:14 row_mask:0xf bank_mask:0xf
	v_fmac_f32_dpp v125, v115, v95 row_newbcast:15 row_mask:0xf bank_mask:0xf
	v_add_f32_e32 v130, v124, v125
	s_waitcnt lgkmcnt(0)
	ds_read_b32 v102, v14 offset:7936
	ds_read_b32 v103, v14 offset:8064
	ds_read_b32 v106, v15 offset:7680
	ds_read_b32 v107, v15 offset:7808
	ds_read_b32 v109, v16 offset:7680
	ds_read_b32 v112, v14 offset:8704
	ds_read_b32 v113, v14 offset:8832
	v_mul_f32_dpp v120, v100, v32 row_newbcast:0 row_mask:0xf bank_mask:0xf
	v_mul_f32_dpp v121, v100, v33 row_newbcast:1 row_mask:0xf bank_mask:0xf
	v_fmac_f32_dpp v120, v100, v34 row_newbcast:2 row_mask:0xf bank_mask:0xf
	v_fmac_f32_dpp v121, v100, v35 row_newbcast:3 row_mask:0xf bank_mask:0xf
	v_fmac_f32_dpp v120, v100, v36 row_newbcast:4 row_mask:0xf bank_mask:0xf
	v_fmac_f32_dpp v121, v100, v37 row_newbcast:5 row_mask:0xf bank_mask:0xf
	v_fmac_f32_dpp v120, v100, v38 row_newbcast:6 row_mask:0xf bank_mask:0xf
	v_fmac_f32_dpp v121, v100, v39 row_newbcast:7 row_mask:0xf bank_mask:0xf
	v_fmac_f32_dpp v120, v100, v40 row_newbcast:8 row_mask:0xf bank_mask:0xf
	v_fmac_f32_dpp v121, v100, v41 row_newbcast:9 row_mask:0xf bank_mask:0xf
	v_fmac_f32_dpp v120, v100, v42 row_newbcast:10 row_mask:0xf bank_mask:0xf
	v_fmac_f32_dpp v121, v100, v43 row_newbcast:11 row_mask:0xf bank_mask:0xf
	v_fmac_f32_dpp v120, v100, v44 row_newbcast:12 row_mask:0xf bank_mask:0xf
	v_fmac_f32_dpp v121, v100, v45 row_newbcast:13 row_mask:0xf bank_mask:0xf
	v_fmac_f32_dpp v120, v100, v46 row_newbcast:14 row_mask:0xf bank_mask:0xf
	v_fmac_f32_dpp v121, v100, v47 row_newbcast:15 row_mask:0xf bank_mask:0xf
	v_fmac_f32_dpp v120, v101, v48 row_newbcast:0 row_mask:0xf bank_mask:0xf
	v_fmac_f32_dpp v121, v101, v49 row_newbcast:1 row_mask:0xf bank_mask:0xf
	v_fmac_f32_dpp v120, v101, v50 row_newbcast:2 row_mask:0xf bank_mask:0xf
	v_fmac_f32_dpp v121, v101, v51 row_newbcast:3 row_mask:0xf bank_mask:0xf
	v_fmac_f32_dpp v120, v101, v52 row_newbcast:4 row_mask:0xf bank_mask:0xf
	v_fmac_f32_dpp v121, v101, v53 row_newbcast:5 row_mask:0xf bank_mask:0xf
	v_fmac_f32_dpp v120, v101, v54 row_newbcast:6 row_mask:0xf bank_mask:0xf
	v_fmac_f32_dpp v121, v101, v55 row_newbcast:7 row_mask:0xf bank_mask:0xf
	v_fmac_f32_dpp v120, v101, v56 row_newbcast:8 row_mask:0xf bank_mask:0xf
	v_fmac_f32_dpp v121, v101, v57 row_newbcast:9 row_mask:0xf bank_mask:0xf
	v_fmac_f32_dpp v120, v101, v58 row_newbcast:10 row_mask:0xf bank_mask:0xf
	v_fmac_f32_dpp v121, v101, v59 row_newbcast:11 row_mask:0xf bank_mask:0xf
	v_fmac_f32_dpp v120, v101, v60 row_newbcast:12 row_mask:0xf bank_mask:0xf
	v_fmac_f32_dpp v121, v101, v61 row_newbcast:13 row_mask:0xf bank_mask:0xf
	v_fmac_f32_dpp v120, v101, v62 row_newbcast:14 row_mask:0xf bank_mask:0xf
	v_fmac_f32_dpp v121, v101, v63 row_newbcast:15 row_mask:0xf bank_mask:0xf
	v_add_f32_e32 v128, v120, v121
	v_mul_f32_dpp v124, v116, v32 row_newbcast:0 row_mask:0xf bank_mask:0xf
	v_mul_f32_dpp v125, v116, v33 row_newbcast:1 row_mask:0xf bank_mask:0xf
	v_permlane32_swap_b32 v129, v128
	v_fmac_f32_dpp v124, v116, v34 row_newbcast:2 row_mask:0xf bank_mask:0xf
	v_fmac_f32_dpp v125, v116, v35 row_newbcast:3 row_mask:0xf bank_mask:0xf
	v_add_f32_dpp v108, -v129, -v128 quad_perm:[0,1,2,3] row_mask:0xc bank_mask:0xf
	v_fmac_f32_dpp v124, v116, v36 row_newbcast:4 row_mask:0xf bank_mask:0xf
	v_fmac_f32_dpp v125, v116, v37 row_newbcast:5 row_mask:0xf bank_mask:0xf
	v_mfma_f32_32x32x2_f32 v[64:79], v104, v108, v[32:47]
	v_fmac_f32_dpp v124, v116, v38 row_newbcast:6 row_mask:0xf bank_mask:0xf
	v_fmac_f32_dpp v125, v116, v39 row_newbcast:7 row_mask:0xf bank_mask:0xf
	v_fmac_f32_dpp v124, v116, v40 row_newbcast:8 row_mask:0xf bank_mask:0xf
	v_fmac_f32_dpp v125, v116, v41 row_newbcast:9 row_mask:0xf bank_mask:0xf
	v_fmac_f32_dpp v124, v116, v42 row_newbcast:10 row_mask:0xf bank_mask:0xf
	v_fmac_f32_dpp v125, v116, v43 row_newbcast:11 row_mask:0xf bank_mask:0xf
	v_fmac_f32_dpp v124, v116, v44 row_newbcast:12 row_mask:0xf bank_mask:0xf
	v_fmac_f32_dpp v125, v116, v45 row_newbcast:13 row_mask:0xf bank_mask:0xf
	v_fmac_f32_dpp v124, v116, v46 row_newbcast:14 row_mask:0xf bank_mask:0xf
	v_fmac_f32_dpp v125, v116, v47 row_newbcast:15 row_mask:0xf bank_mask:0xf
	v_fmac_f32_dpp v124, v117, v48 row_newbcast:0 row_mask:0xf bank_mask:0xf
	v_fmac_f32_dpp v125, v117, v49 row_newbcast:1 row_mask:0xf bank_mask:0xf
	v_fmac_f32_dpp v124, v117, v50 row_newbcast:2 row_mask:0xf bank_mask:0xf
	v_fmac_f32_dpp v125, v117, v51 row_newbcast:3 row_mask:0xf bank_mask:0xf
	v_mfma_f32_32x32x2_f32 v[80:95], v105, v108, v[48:63]
	v_fmac_f32_dpp v124, v117, v52 row_newbcast:4 row_mask:0xf bank_mask:0xf
	v_fmac_f32_dpp v125, v117, v53 row_newbcast:5 row_mask:0xf bank_mask:0xf
	v_fmac_f32_dpp v124, v117, v54 row_newbcast:6 row_mask:0xf bank_mask:0xf
	v_fmac_f32_dpp v125, v117, v55 row_newbcast:7 row_mask:0xf bank_mask:0xf
	v_fmac_f32_dpp v124, v117, v56 row_newbcast:8 row_mask:0xf bank_mask:0xf
	v_fmac_f32_dpp v125, v117, v57 row_newbcast:9 row_mask:0xf bank_mask:0xf
	v_fmac_f32_dpp v124, v117, v58 row_newbcast:10 row_mask:0xf bank_mask:0xf
	v_fmac_f32_dpp v125, v117, v59 row_newbcast:11 row_mask:0xf bank_mask:0xf
	v_fmac_f32_dpp v124, v117, v60 row_newbcast:12 row_mask:0xf bank_mask:0xf
	v_fmac_f32_dpp v125, v117, v61 row_newbcast:13 row_mask:0xf bank_mask:0xf
	v_fmac_f32_dpp v124, v117, v62 row_newbcast:14 row_mask:0xf bank_mask:0xf
	v_fmac_f32_dpp v125, v117, v63 row_newbcast:15 row_mask:0xf bank_mask:0xf
	v_add_f32_e32 v131, v124, v125
	s_nop 1
	v_permlane32_swap_b32 v130, v131
	v_add_f32_e32 v133, v130, v131
	v_cvt_pk_bf16_f32 v133, v133, v133
	global_store_short v13, v133, s[16:17]
	s_add_u32 s16, s16, s20
	s_addc_u32 s17, s17, s21
	s_waitcnt lgkmcnt(0)
	ds_read_b32 v100, v14 offset:9472
	ds_read_b32 v101, v14 offset:9600
	ds_read_b32 v104, v15 offset:9216
	ds_read_b32 v105, v15 offset:9344
	ds_read_b32 v108, v16 offset:9216
	ds_read_b32 v114, v14 offset:10240
	ds_read_b32 v115, v14 offset:10368
	v_mul_f32_dpp v120, v102, v64 row_newbcast:0 row_mask:0xf bank_mask:0xf
	v_mul_f32_dpp v121, v102, v65 row_newbcast:1 row_mask:0xf bank_mask:0xf
	v_fmac_f32_dpp v120, v102, v66 row_newbcast:2 row_mask:0xf bank_mask:0xf
	v_fmac_f32_dpp v121, v102, v67 row_newbcast:3 row_mask:0xf bank_mask:0xf
	v_fmac_f32_dpp v120, v102, v68 row_newbcast:4 row_mask:0xf bank_mask:0xf
	v_fmac_f32_dpp v121, v102, v69 row_newbcast:5 row_mask:0xf bank_mask:0xf
	v_fmac_f32_dpp v120, v102, v70 row_newbcast:6 row_mask:0xf bank_mask:0xf
	v_fmac_f32_dpp v121, v102, v71 row_newbcast:7 row_mask:0xf bank_mask:0xf
	v_fmac_f32_dpp v120, v102, v72 row_newbcast:8 row_mask:0xf bank_mask:0xf
	v_fmac_f32_dpp v121, v102, v73 row_newbcast:9 row_mask:0xf bank_mask:0xf
	v_fmac_f32_dpp v120, v102, v74 row_newbcast:10 row_mask:0xf bank_mask:0xf
	v_fmac_f32_dpp v121, v102, v75 row_newbcast:11 row_mask:0xf bank_mask:0xf
	v_fmac_f32_dpp v120, v102, v76 row_newbcast:12 row_mask:0xf bank_mask:0xf
	v_fmac_f32_dpp v121, v102, v77 row_newbcast:13 row_mask:0xf bank_mask:0xf
	v_fmac_f32_dpp v120, v102, v78 row_newbcast:14 row_mask:0xf bank_mask:0xf
	v_fmac_f32_dpp v121, v102, v79 row_newbcast:15 row_mask:0xf bank_mask:0xf
	v_fmac_f32_dpp v120, v103, v80 row_newbcast:0 row_mask:0xf bank_mask:0xf
	v_fmac_f32_dpp v121, v103, v81 row_newbcast:1 row_mask:0xf bank_mask:0xf
	v_fmac_f32_dpp v120, v103, v82 row_newbcast:2 row_mask:0xf bank_mask:0xf
	v_fmac_f32_dpp v121, v103, v83 row_newbcast:3 row_mask:0xf bank_mask:0xf
	v_fmac_f32_dpp v120, v103, v84 row_newbcast:4 row_mask:0xf bank_mask:0xf
	v_fmac_f32_dpp v121, v103, v85 row_newbcast:5 row_mask:0xf bank_mask:0xf
	v_fmac_f32_dpp v120, v103, v86 row_newbcast:6 row_mask:0xf bank_mask:0xf
	v_fmac_f32_dpp v121, v103, v87 row_newbcast:7 row_mask:0xf bank_mask:0xf
	v_fmac_f32_dpp v120, v103, v88 row_newbcast:8 row_mask:0xf bank_mask:0xf
	v_fmac_f32_dpp v121, v103, v89 row_newbcast:9 row_mask:0xf bank_mask:0xf
	v_fmac_f32_dpp v120, v103, v90 row_newbcast:10 row_mask:0xf bank_mask:0xf
	v_fmac_f32_dpp v121, v103, v91 row_newbcast:11 row_mask:0xf bank_mask:0xf
	v_fmac_f32_dpp v120, v103, v92 row_newbcast:12 row_mask:0xf bank_mask:0xf
	v_fmac_f32_dpp v121, v103, v93 row_newbcast:13 row_mask:0xf bank_mask:0xf
	v_fmac_f32_dpp v120, v103, v94 row_newbcast:14 row_mask:0xf bank_mask:0xf
	v_fmac_f32_dpp v121, v103, v95 row_newbcast:15 row_mask:0xf bank_mask:0xf
	v_add_f32_e32 v128, v120, v121
	v_mul_f32_dpp v124, v110, v64 row_newbcast:0 row_mask:0xf bank_mask:0xf
	v_mul_f32_dpp v125, v110, v65 row_newbcast:1 row_mask:0xf bank_mask:0xf
	v_permlane32_swap_b32 v129, v128
	v_fmac_f32_dpp v124, v110, v66 row_newbcast:2 row_mask:0xf bank_mask:0xf
	v_fmac_f32_dpp v125, v110, v67 row_newbcast:3 row_mask:0xf bank_mask:0xf
	v_add_f32_dpp v109, -v129, -v128 quad_perm:[0,1,2,3] row_mask:0xc bank_mask:0xf
	v_fmac_f32_dpp v124, v110, v68 row_newbcast:4 row_mask:0xf bank_mask:0xf
	v_fmac_f32_dpp v125, v110, v69 row_newbcast:5 row_mask:0xf bank_mask:0xf
	v_mfma_f32_32x32x2_f32 v[32:47], v106, v109, v[64:79]
	v_fmac_f32_dpp v124, v110, v70 row_newbcast:6 row_mask:0xf bank_mask:0xf
	v_fmac_f32_dpp v125, v110, v71 row_newbcast:7 row_mask:0xf bank_mask:0xf
	v_fmac_f32_dpp v124, v110, v72 row_newbcast:8 row_mask:0xf bank_mask:0xf
	v_fmac_f32_dpp v125, v110, v73 row_newbcast:9 row_mask:0xf bank_mask:0xf
	v_fmac_f32_dpp v124, v110, v74 row_newbcast:10 row_mask:0xf bank_mask:0xf
	v_fmac_f32_dpp v125, v110, v75 row_newbcast:11 row_mask:0xf bank_mask:0xf
	v_fmac_f32_dpp v124, v110, v76 row_newbcast:12 row_mask:0xf bank_mask:0xf
	v_fmac_f32_dpp v125, v110, v77 row_newbcast:13 row_mask:0xf bank_mask:0xf
	v_fmac_f32_dpp v124, v110, v78 row_newbcast:14 row_mask:0xf bank_mask:0xf
	v_fmac_f32_dpp v125, v110, v79 row_newbcast:15 row_mask:0xf bank_mask:0xf
	v_fmac_f32_dpp v124, v111, v80 row_newbcast:0 row_mask:0xf bank_mask:0xf
	v_fmac_f32_dpp v125, v111, v81 row_newbcast:1 row_mask:0xf bank_mask:0xf
	v_fmac_f32_dpp v124, v111, v82 row_newbcast:2 row_mask:0xf bank_mask:0xf
	v_fmac_f32_dpp v125, v111, v83 row_newbcast:3 row_mask:0xf bank_mask:0xf
	v_mfma_f32_32x32x2_f32 v[48:63], v107, v109, v[80:95]
	v_fmac_f32_dpp v124, v111, v84 row_newbcast:4 row_mask:0xf bank_mask:0xf
	v_fmac_f32_dpp v125, v111, v85 row_newbcast:5 row_mask:0xf bank_mask:0xf
	v_fmac_f32_dpp v124, v111, v86 row_newbcast:6 row_mask:0xf bank_mask:0xf
	v_fmac_f32_dpp v125, v111, v87 row_newbcast:7 row_mask:0xf bank_mask:0xf
	v_fmac_f32_dpp v124, v111, v88 row_newbcast:8 row_mask:0xf bank_mask:0xf
	v_fmac_f32_dpp v125, v111, v89 row_newbcast:9 row_mask:0xf bank_mask:0xf
	v_fmac_f32_dpp v124, v111, v90 row_newbcast:10 row_mask:0xf bank_mask:0xf
	v_fmac_f32_dpp v125, v111, v91 row_newbcast:11 row_mask:0xf bank_mask:0xf
	v_fmac_f32_dpp v124, v111, v92 row_newbcast:12 row_mask:0xf bank_mask:0xf
	v_fmac_f32_dpp v125, v111, v93 row_newbcast:13 row_mask:0xf bank_mask:0xf
	v_fmac_f32_dpp v124, v111, v94 row_newbcast:14 row_mask:0xf bank_mask:0xf
	v_fmac_f32_dpp v125, v111, v95 row_newbcast:15 row_mask:0xf bank_mask:0xf
	v_add_f32_e32 v130, v124, v125
	s_waitcnt lgkmcnt(0)
	ds_read_b32 v102, v14 offset:11008
	ds_read_b32 v103, v14 offset:11136
	ds_read_b32 v106, v15 offset:10752
	ds_read_b32 v107, v15 offset:10880
	ds_read_b32 v109, v16 offset:10752
	ds_read_b32 v116, v14 offset:11776
	ds_read_b32 v117, v14 offset:11904
	ds_read_b32 v118, v14 offset:10752
	ds_read_b32 v119, v14 offset:10880
	v_mul_f32_dpp v120, v100, v32 row_newbcast:0 row_mask:0xf bank_mask:0xf
	v_mul_f32_dpp v121, v100, v33 row_newbcast:1 row_mask:0xf bank_mask:0xf
	v_fmac_f32_dpp v120, v100, v34 row_newbcast:2 row_mask:0xf bank_mask:0xf
	v_fmac_f32_dpp v121, v100, v35 row_newbcast:3 row_mask:0xf bank_mask:0xf
	v_fmac_f32_dpp v120, v100, v36 row_newbcast:4 row_mask:0xf bank_mask:0xf
	v_fmac_f32_dpp v121, v100, v37 row_newbcast:5 row_mask:0xf bank_mask:0xf
	v_fmac_f32_dpp v120, v100, v38 row_newbcast:6 row_mask:0xf bank_mask:0xf
	v_fmac_f32_dpp v121, v100, v39 row_newbcast:7 row_mask:0xf bank_mask:0xf
	v_fmac_f32_dpp v120, v100, v40 row_newbcast:8 row_mask:0xf bank_mask:0xf
	v_fmac_f32_dpp v121, v100, v41 row_newbcast:9 row_mask:0xf bank_mask:0xf
	v_fmac_f32_dpp v120, v100, v42 row_newbcast:10 row_mask:0xf bank_mask:0xf
	v_fmac_f32_dpp v121, v100, v43 row_newbcast:11 row_mask:0xf bank_mask:0xf
	v_fmac_f32_dpp v120, v100, v44 row_newbcast:12 row_mask:0xf bank_mask:0xf
	v_fmac_f32_dpp v121, v100, v45 row_newbcast:13 row_mask:0xf bank_mask:0xf
	v_fmac_f32_dpp v120, v100, v46 row_newbcast:14 row_mask:0xf bank_mask:0xf
	v_fmac_f32_dpp v121, v100, v47 row_newbcast:15 row_mask:0xf bank_mask:0xf
	v_fmac_f32_dpp v120, v101, v48 row_newbcast:0 row_mask:0xf bank_mask:0xf
	v_fmac_f32_dpp v121, v101, v49 row_newbcast:1 row_mask:0xf bank_mask:0xf
	v_fmac_f32_dpp v120, v101, v50 row_newbcast:2 row_mask:0xf bank_mask:0xf
	v_fmac_f32_dpp v121, v101, v51 row_newbcast:3 row_mask:0xf bank_mask:0xf
	v_fmac_f32_dpp v120, v101, v52 row_newbcast:4 row_mask:0xf bank_mask:0xf
	v_fmac_f32_dpp v121, v101, v53 row_newbcast:5 row_mask:0xf bank_mask:0xf
	v_fmac_f32_dpp v120, v101, v54 row_newbcast:6 row_mask:0xf bank_mask:0xf
	v_fmac_f32_dpp v121, v101, v55 row_newbcast:7 row_mask:0xf bank_mask:0xf
	v_fmac_f32_dpp v120, v101, v56 row_newbcast:8 row_mask:0xf bank_mask:0xf
	v_fmac_f32_dpp v121, v101, v57 row_newbcast:9 row_mask:0xf bank_mask:0xf
	v_fmac_f32_dpp v120, v101, v58 row_newbcast:10 row_mask:0xf bank_mask:0xf
	v_fmac_f32_dpp v121, v101, v59 row_newbcast:11 row_mask:0xf bank_mask:0xf
	v_fmac_f32_dpp v120, v101, v60 row_newbcast:12 row_mask:0xf bank_mask:0xf
	v_fmac_f32_dpp v121, v101, v61 row_newbcast:13 row_mask:0xf bank_mask:0xf
	v_fmac_f32_dpp v120, v101, v62 row_newbcast:14 row_mask:0xf bank_mask:0xf
	v_fmac_f32_dpp v121, v101, v63 row_newbcast:15 row_mask:0xf bank_mask:0xf
	v_add_f32_e32 v128, v120, v121
	v_mul_f32_dpp v124, v112, v32 row_newbcast:0 row_mask:0xf bank_mask:0xf
	v_mul_f32_dpp v125, v112, v33 row_newbcast:1 row_mask:0xf bank_mask:0xf
	v_permlane32_swap_b32 v129, v128
	v_fmac_f32_dpp v124, v112, v34 row_newbcast:2 row_mask:0xf bank_mask:0xf
	v_fmac_f32_dpp v125, v112, v35 row_newbcast:3 row_mask:0xf bank_mask:0xf
	v_add_f32_dpp v108, -v129, -v128 quad_perm:[0,1,2,3] row_mask:0xc bank_mask:0xf
	v_fmac_f32_dpp v124, v112, v36 row_newbcast:4 row_mask:0xf bank_mask:0xf
	v_fmac_f32_dpp v125, v112, v37 row_newbcast:5 row_mask:0xf bank_mask:0xf
	v_mfma_f32_32x32x2_f32 v[64:79], v104, v108, v[32:47]
	v_fmac_f32_dpp v124, v112, v38 row_newbcast:6 row_mask:0xf bank_mask:0xf
	v_fmac_f32_dpp v125, v112, v39 row_newbcast:7 row_mask:0xf bank_mask:0xf
	v_fmac_f32_dpp v124, v112, v40 row_newbcast:8 row_mask:0xf bank_mask:0xf
	v_fmac_f32_dpp v125, v112, v41 row_newbcast:9 row_mask:0xf bank_mask:0xf
	v_fmac_f32_dpp v124, v112, v42 row_newbcast:10 row_mask:0xf bank_mask:0xf
	v_fmac_f32_dpp v125, v112, v43 row_newbcast:11 row_mask:0xf bank_mask:0xf
	v_fmac_f32_dpp v124, v112, v44 row_newbcast:12 row_mask:0xf bank_mask:0xf
	v_fmac_f32_dpp v125, v112, v45 row_newbcast:13 row_mask:0xf bank_mask:0xf
	v_fmac_f32_dpp v124, v112, v46 row_newbcast:14 row_mask:0xf bank_mask:0xf
	v_fmac_f32_dpp v125, v112, v47 row_newbcast:15 row_mask:0xf bank_mask:0xf
	v_fmac_f32_dpp v124, v113, v48 row_newbcast:0 row_mask:0xf bank_mask:0xf
	v_fmac_f32_dpp v125, v113, v49 row_newbcast:1 row_mask:0xf bank_mask:0xf
	v_fmac_f32_dpp v124, v113, v50 row_newbcast:2 row_mask:0xf bank_mask:0xf
	v_fmac_f32_dpp v125, v113, v51 row_newbcast:3 row_mask:0xf bank_mask:0xf
	v_mfma_f32_32x32x2_f32 v[80:95], v105, v108, v[48:63]
	v_fmac_f32_dpp v124, v113, v52 row_newbcast:4 row_mask:0xf bank_mask:0xf
	v_fmac_f32_dpp v125, v113, v53 row_newbcast:5 row_mask:0xf bank_mask:0xf
	v_fmac_f32_dpp v124, v113, v54 row_newbcast:6 row_mask:0xf bank_mask:0xf
	v_fmac_f32_dpp v125, v113, v55 row_newbcast:7 row_mask:0xf bank_mask:0xf
	v_fmac_f32_dpp v124, v113, v56 row_newbcast:8 row_mask:0xf bank_mask:0xf
	v_fmac_f32_dpp v125, v113, v57 row_newbcast:9 row_mask:0xf bank_mask:0xf
	v_fmac_f32_dpp v124, v113, v58 row_newbcast:10 row_mask:0xf bank_mask:0xf
	v_fmac_f32_dpp v125, v113, v59 row_newbcast:11 row_mask:0xf bank_mask:0xf
	v_fmac_f32_dpp v124, v113, v60 row_newbcast:12 row_mask:0xf bank_mask:0xf
	v_fmac_f32_dpp v125, v113, v61 row_newbcast:13 row_mask:0xf bank_mask:0xf
	v_fmac_f32_dpp v124, v113, v62 row_newbcast:14 row_mask:0xf bank_mask:0xf
	v_fmac_f32_dpp v125, v113, v63 row_newbcast:15 row_mask:0xf bank_mask:0xf
	v_add_f32_e32 v131, v124, v125
	s_nop 1
	v_permlane32_swap_b32 v130, v131
	v_add_f32_e32 v133, v130, v131
	v_cvt_pk_bf16_f32 v133, v133, v133
	global_store_short v13, v133, s[16:17]
	s_add_u32 s16, s16, s20
	s_addc_u32 s17, s17, s21
	s_waitcnt lgkmcnt(0)
	ds_read_b32 v100, v14 offset:12544
	ds_read_b32 v101, v14 offset:12672
	ds_read_b32 v104, v15 offset:12288
	ds_read_b32 v105, v15 offset:12416
	ds_read_b32 v108, v16 offset:12288
	ds_read_b32 v110, v14 offset:13312
	ds_read_b32 v111, v14 offset:13440
	v_mul_f32_dpp v120, v102, v64 row_newbcast:0 row_mask:0xf bank_mask:0xf
	v_mul_f32_dpp v121, v102, v65 row_newbcast:1 row_mask:0xf bank_mask:0xf
	v_fmac_f32_dpp v120, v102, v66 row_newbcast:2 row_mask:0xf bank_mask:0xf
	v_fmac_f32_dpp v121, v102, v67 row_newbcast:3 row_mask:0xf bank_mask:0xf
	v_fmac_f32_dpp v120, v102, v68 row_newbcast:4 row_mask:0xf bank_mask:0xf
	v_fmac_f32_dpp v121, v102, v69 row_newbcast:5 row_mask:0xf bank_mask:0xf
	v_fmac_f32_dpp v120, v102, v70 row_newbcast:6 row_mask:0xf bank_mask:0xf
	v_fmac_f32_dpp v121, v102, v71 row_newbcast:7 row_mask:0xf bank_mask:0xf
	v_fmac_f32_dpp v120, v102, v72 row_newbcast:8 row_mask:0xf bank_mask:0xf
	v_fmac_f32_dpp v121, v102, v73 row_newbcast:9 row_mask:0xf bank_mask:0xf
	v_fmac_f32_dpp v120, v102, v74 row_newbcast:10 row_mask:0xf bank_mask:0xf
	v_fmac_f32_dpp v121, v102, v75 row_newbcast:11 row_mask:0xf bank_mask:0xf
	v_fmac_f32_dpp v120, v102, v76 row_newbcast:12 row_mask:0xf bank_mask:0xf
	v_fmac_f32_dpp v121, v102, v77 row_newbcast:13 row_mask:0xf bank_mask:0xf
	v_fmac_f32_dpp v120, v102, v78 row_newbcast:14 row_mask:0xf bank_mask:0xf
	v_fmac_f32_dpp v121, v102, v79 row_newbcast:15 row_mask:0xf bank_mask:0xf
	v_fmac_f32_dpp v120, v103, v80 row_newbcast:0 row_mask:0xf bank_mask:0xf
	v_fmac_f32_dpp v121, v103, v81 row_newbcast:1 row_mask:0xf bank_mask:0xf
	v_fmac_f32_dpp v120, v103, v82 row_newbcast:2 row_mask:0xf bank_mask:0xf
	v_fmac_f32_dpp v121, v103, v83 row_newbcast:3 row_mask:0xf bank_mask:0xf
	v_fmac_f32_dpp v120, v103, v84 row_newbcast:4 row_mask:0xf bank_mask:0xf
	v_fmac_f32_dpp v121, v103, v85 row_newbcast:5 row_mask:0xf bank_mask:0xf
	v_fmac_f32_dpp v120, v103, v86 row_newbcast:6 row_mask:0xf bank_mask:0xf
	v_fmac_f32_dpp v121, v103, v87 row_newbcast:7 row_mask:0xf bank_mask:0xf
	v_fmac_f32_dpp v120, v103, v88 row_newbcast:8 row_mask:0xf bank_mask:0xf
	v_fmac_f32_dpp v121, v103, v89 row_newbcast:9 row_mask:0xf bank_mask:0xf
	v_fmac_f32_dpp v120, v103, v90 row_newbcast:10 row_mask:0xf bank_mask:0xf
	v_fmac_f32_dpp v121, v103, v91 row_newbcast:11 row_mask:0xf bank_mask:0xf
	v_fmac_f32_dpp v120, v103, v92 row_newbcast:12 row_mask:0xf bank_mask:0xf
	v_fmac_f32_dpp v121, v103, v93 row_newbcast:13 row_mask:0xf bank_mask:0xf
	v_fmac_f32_dpp v120, v103, v94 row_newbcast:14 row_mask:0xf bank_mask:0xf
	v_fmac_f32_dpp v121, v103, v95 row_newbcast:15 row_mask:0xf bank_mask:0xf
	v_add_f32_e32 v128, v120, v121
	v_mul_f32_dpp v124, v114, v64 row_newbcast:0 row_mask:0xf bank_mask:0xf
	v_mul_f32_dpp v125, v114, v65 row_newbcast:1 row_mask:0xf bank_mask:0xf
	v_permlane32_swap_b32 v129, v128
	v_fmac_f32_dpp v124, v114, v66 row_newbcast:2 row_mask:0xf bank_mask:0xf
	v_fmac_f32_dpp v125, v114, v67 row_newbcast:3 row_mask:0xf bank_mask:0xf
	v_add_f32_dpp v109, -v129, -v128 quad_perm:[0,1,2,3] row_mask:0xc bank_mask:0xf
	v_fmac_f32_dpp v124, v114, v68 row_newbcast:4 row_mask:0xf bank_mask:0xf
	v_fmac_f32_dpp v125, v114, v69 row_newbcast:5 row_mask:0xf bank_mask:0xf
	v_mfma_f32_32x32x2_f32 v[32:47], v106, v109, v[64:79]
	v_fmac_f32_dpp v124, v114, v70 row_newbcast:6 row_mask:0xf bank_mask:0xf
	v_fmac_f32_dpp v125, v114, v71 row_newbcast:7 row_mask:0xf bank_mask:0xf
	v_fmac_f32_dpp v124, v114, v72 row_newbcast:8 row_mask:0xf bank_mask:0xf
	v_fmac_f32_dpp v125, v114, v73 row_newbcast:9 row_mask:0xf bank_mask:0xf
	v_fmac_f32_dpp v124, v114, v74 row_newbcast:10 row_mask:0xf bank_mask:0xf
	v_fmac_f32_dpp v125, v114, v75 row_newbcast:11 row_mask:0xf bank_mask:0xf
	v_fmac_f32_dpp v124, v114, v76 row_newbcast:12 row_mask:0xf bank_mask:0xf
	v_fmac_f32_dpp v125, v114, v77 row_newbcast:13 row_mask:0xf bank_mask:0xf
	v_fmac_f32_dpp v124, v114, v78 row_newbcast:14 row_mask:0xf bank_mask:0xf
	v_fmac_f32_dpp v125, v114, v79 row_newbcast:15 row_mask:0xf bank_mask:0xf
	v_fmac_f32_dpp v124, v115, v80 row_newbcast:0 row_mask:0xf bank_mask:0xf
	v_fmac_f32_dpp v125, v115, v81 row_newbcast:1 row_mask:0xf bank_mask:0xf
	v_fmac_f32_dpp v124, v115, v82 row_newbcast:2 row_mask:0xf bank_mask:0xf
	v_fmac_f32_dpp v125, v115, v83 row_newbcast:3 row_mask:0xf bank_mask:0xf
	v_mfma_f32_32x32x2_f32 v[48:63], v107, v109, v[80:95]
	v_fmac_f32_dpp v124, v115, v84 row_newbcast:4 row_mask:0xf bank_mask:0xf
	v_fmac_f32_dpp v125, v115, v85 row_newbcast:5 row_mask:0xf bank_mask:0xf
	v_fmac_f32_dpp v124, v115, v86 row_newbcast:6 row_mask:0xf bank_mask:0xf
	v_fmac_f32_dpp v125, v115, v87 row_newbcast:7 row_mask:0xf bank_mask:0xf
	v_fmac_f32_dpp v124, v115, v88 row_newbcast:8 row_mask:0xf bank_mask:0xf
	v_fmac_f32_dpp v125, v115, v89 row_newbcast:9 row_mask:0xf bank_mask:0xf
	v_fmac_f32_dpp v124, v115, v90 row_newbcast:10 row_mask:0xf bank_mask:0xf
	v_fmac_f32_dpp v125, v115, v91 row_newbcast:11 row_mask:0xf bank_mask:0xf
	v_fmac_f32_dpp v124, v115, v92 row_newbcast:12 row_mask:0xf bank_mask:0xf
	v_fmac_f32_dpp v125, v115, v93 row_newbcast:13 row_mask:0xf bank_mask:0xf
	v_fmac_f32_dpp v124, v115, v94 row_newbcast:14 row_mask:0xf bank_mask:0xf
	v_fmac_f32_dpp v125, v115, v95 row_newbcast:15 row_mask:0xf bank_mask:0xf
	v_add_f32_e32 v130, v124, v125
	v_mul_f32_dpp v124, v116, v32 row_newbcast:0 row_mask:0xf bank_mask:0xf
	v_mul_f32_dpp v125, v116, v33 row_newbcast:1 row_mask:0xf bank_mask:0xf
	v_fmac_f32_dpp v124, v116, v34 row_newbcast:2 row_mask:0xf bank_mask:0xf
	v_fmac_f32_dpp v125, v116, v35 row_newbcast:3 row_mask:0xf bank_mask:0xf
	v_fmac_f32_dpp v124, v116, v36 row_newbcast:4 row_mask:0xf bank_mask:0xf
	v_fmac_f32_dpp v125, v116, v37 row_newbcast:5 row_mask:0xf bank_mask:0xf
	v_fmac_f32_dpp v124, v116, v38 row_newbcast:6 row_mask:0xf bank_mask:0xf
	v_fmac_f32_dpp v125, v116, v39 row_newbcast:7 row_mask:0xf bank_mask:0xf
	v_fmac_f32_dpp v124, v116, v40 row_newbcast:8 row_mask:0xf bank_mask:0xf
	v_fmac_f32_dpp v125, v116, v41 row_newbcast:9 row_mask:0xf bank_mask:0xf
	v_fmac_f32_dpp v124, v116, v42 row_newbcast:10 row_mask:0xf bank_mask:0xf
	v_fmac_f32_dpp v125, v116, v43 row_newbcast:11 row_mask:0xf bank_mask:0xf
	v_fmac_f32_dpp v124, v116, v44 row_newbcast:12 row_mask:0xf bank_mask:0xf
	v_fmac_f32_dpp v125, v116, v45 row_newbcast:13 row_mask:0xf bank_mask:0xf
	v_fmac_f32_dpp v124, v116, v46 row_newbcast:14 row_mask:0xf bank_mask:0xf
	v_fmac_f32_dpp v125, v116, v47 row_newbcast:15 row_mask:0xf bank_mask:0xf
	v_fmac_f32_dpp v124, v117, v48 row_newbcast:0 row_mask:0xf bank_mask:0xf
	v_fmac_f32_dpp v125, v117, v49 row_newbcast:1 row_mask:0xf bank_mask:0xf
	v_fmac_f32_dpp v124, v117, v50 row_newbcast:2 row_mask:0xf bank_mask:0xf
	v_fmac_f32_dpp v125, v117, v51 row_newbcast:3 row_mask:0xf bank_mask:0xf
	v_fmac_f32_dpp v124, v117, v52 row_newbcast:4 row_mask:0xf bank_mask:0xf
	v_fmac_f32_dpp v125, v117, v53 row_newbcast:5 row_mask:0xf bank_mask:0xf
	v_fmac_f32_dpp v124, v117, v54 row_newbcast:6 row_mask:0xf bank_mask:0xf
	v_fmac_f32_dpp v125, v117, v55 row_newbcast:7 row_mask:0xf bank_mask:0xf
	v_fmac_f32_dpp v124, v117, v56 row_newbcast:8 row_mask:0xf bank_mask:0xf
	v_fmac_f32_dpp v125, v117, v57 row_newbcast:9 row_mask:0xf bank_mask:0xf
	v_fmac_f32_dpp v124, v117, v58 row_newbcast:10 row_mask:0xf bank_mask:0xf
	v_fmac_f32_dpp v125, v117, v59 row_newbcast:11 row_mask:0xf bank_mask:0xf
	v_fmac_f32_dpp v124, v117, v60 row_newbcast:12 row_mask:0xf bank_mask:0xf
	v_fmac_f32_dpp v125, v117, v61 row_newbcast:13 row_mask:0xf bank_mask:0xf
	v_fmac_f32_dpp v124, v117, v62 row_newbcast:14 row_mask:0xf bank_mask:0xf
	v_fmac_f32_dpp v125, v117, v63 row_newbcast:15 row_mask:0xf bank_mask:0xf
	v_add_f32_e32 v131, v124, v125
	s_nop 1
	v_permlane32_swap_b32 v130, v131
	v_add_f32_e32 v133, v130, v131
	v_cvt_pk_bf16_f32 v133, v133, v133
	global_store_short v13, v133, s[16:17]
	s_add_u32 s16, s16, s20
	s_addc_u32 s17, s17, s21
	v_mul_f32_dpp v32, v118, v32 row_newbcast:0 row_mask:0xf bank_mask:0xf
	v_mul_f32_dpp v33, v118, v33 row_newbcast:1 row_mask:0xf bank_mask:0xf
	v_mul_f32_dpp v34, v118, v34 row_newbcast:2 row_mask:0xf bank_mask:0xf
	v_mul_f32_dpp v35, v118, v35 row_newbcast:3 row_mask:0xf bank_mask:0xf
	v_mul_f32_dpp v36, v118, v36 row_newbcast:4 row_mask:0xf bank_mask:0xf
	v_mul_f32_dpp v37, v118, v37 row_newbcast:5 row_mask:0xf bank_mask:0xf
	v_mul_f32_dpp v38, v118, v38 row_newbcast:6 row_mask:0xf bank_mask:0xf
	v_mul_f32_dpp v39, v118, v39 row_newbcast:7 row_mask:0xf bank_mask:0xf
	v_mul_f32_dpp v40, v118, v40 row_newbcast:8 row_mask:0xf bank_mask:0xf
	v_mul_f32_dpp v41, v118, v41 row_newbcast:9 row_mask:0xf bank_mask:0xf
	v_mul_f32_dpp v42, v118, v42 row_newbcast:10 row_mask:0xf bank_mask:0xf
	v_mul_f32_dpp v43, v118, v43 row_newbcast:11 row_mask:0xf bank_mask:0xf
	v_mul_f32_dpp v44, v118, v44 row_newbcast:12 row_mask:0xf bank_mask:0xf
	v_mul_f32_dpp v45, v118, v45 row_newbcast:13 row_mask:0xf bank_mask:0xf
	v_mul_f32_dpp v46, v118, v46 row_newbcast:14 row_mask:0xf bank_mask:0xf
	v_mul_f32_dpp v47, v118, v47 row_newbcast:15 row_mask:0xf bank_mask:0xf
	v_mul_f32_dpp v48, v119, v48 row_newbcast:0 row_mask:0xf bank_mask:0xf
	v_mul_f32_dpp v49, v119, v49 row_newbcast:1 row_mask:0xf bank_mask:0xf
	v_mul_f32_dpp v50, v119, v50 row_newbcast:2 row_mask:0xf bank_mask:0xf
	v_mul_f32_dpp v51, v119, v51 row_newbcast:3 row_mask:0xf bank_mask:0xf
	v_mul_f32_dpp v52, v119, v52 row_newbcast:4 row_mask:0xf bank_mask:0xf
	v_mul_f32_dpp v53, v119, v53 row_newbcast:5 row_mask:0xf bank_mask:0xf
	v_mul_f32_dpp v54, v119, v54 row_newbcast:6 row_mask:0xf bank_mask:0xf
	v_mul_f32_dpp v55, v119, v55 row_newbcast:7 row_mask:0xf bank_mask:0xf
	v_mul_f32_dpp v56, v119, v56 row_newbcast:8 row_mask:0xf bank_mask:0xf
	v_mul_f32_dpp v57, v119, v57 row_newbcast:9 row_mask:0xf bank_mask:0xf
	v_mul_f32_dpp v58, v119, v58 row_newbcast:10 row_mask:0xf bank_mask:0xf
	v_mul_f32_dpp v59, v119, v59 row_newbcast:11 row_mask:0xf bank_mask:0xf
	v_mul_f32_dpp v60, v119, v60 row_newbcast:12 row_mask:0xf bank_mask:0xf
	v_mul_f32_dpp v61, v119, v61 row_newbcast:13 row_mask:0xf bank_mask:0xf
	v_mul_f32_dpp v62, v119, v62 row_newbcast:14 row_mask:0xf bank_mask:0xf
	v_mul_f32_dpp v63, v119, v63 row_newbcast:15 row_mask:0xf bank_mask:0xf
	s_waitcnt lgkmcnt(0)
	ds_read_b32 v102, v14 offset:14080
	ds_read_b32 v103, v14 offset:14208
	ds_read_b32 v106, v15 offset:13824
	ds_read_b32 v107, v15 offset:13952
	ds_read_b32 v109, v16 offset:13824
	ds_read_b32 v112, v14 offset:14848
	ds_read_b32 v113, v14 offset:14976
	v_mul_f32_dpp v120, v100, v32 row_newbcast:0 row_mask:0xf bank_mask:0xf
	v_mul_f32_dpp v121, v100, v33 row_newbcast:1 row_mask:0xf bank_mask:0xf
	v_fmac_f32_dpp v120, v100, v34 row_newbcast:2 row_mask:0xf bank_mask:0xf
	v_fmac_f32_dpp v121, v100, v35 row_newbcast:3 row_mask:0xf bank_mask:0xf
	v_fmac_f32_dpp v120, v100, v36 row_newbcast:4 row_mask:0xf bank_mask:0xf
	v_fmac_f32_dpp v121, v100, v37 row_newbcast:5 row_mask:0xf bank_mask:0xf
	v_fmac_f32_dpp v120, v100, v38 row_newbcast:6 row_mask:0xf bank_mask:0xf
	v_fmac_f32_dpp v121, v100, v39 row_newbcast:7 row_mask:0xf bank_mask:0xf
	v_fmac_f32_dpp v120, v100, v40 row_newbcast:8 row_mask:0xf bank_mask:0xf
	v_fmac_f32_dpp v121, v100, v41 row_newbcast:9 row_mask:0xf bank_mask:0xf
	v_fmac_f32_dpp v120, v100, v42 row_newbcast:10 row_mask:0xf bank_mask:0xf
	v_fmac_f32_dpp v121, v100, v43 row_newbcast:11 row_mask:0xf bank_mask:0xf
	v_fmac_f32_dpp v120, v100, v44 row_newbcast:12 row_mask:0xf bank_mask:0xf
	v_fmac_f32_dpp v121, v100, v45 row_newbcast:13 row_mask:0xf bank_mask:0xf
	v_fmac_f32_dpp v120, v100, v46 row_newbcast:14 row_mask:0xf bank_mask:0xf
	v_fmac_f32_dpp v121, v100, v47 row_newbcast:15 row_mask:0xf bank_mask:0xf
	v_fmac_f32_dpp v120, v101, v48 row_newbcast:0 row_mask:0xf bank_mask:0xf
	v_fmac_f32_dpp v121, v101, v49 row_newbcast:1 row_mask:0xf bank_mask:0xf
	v_fmac_f32_dpp v120, v101, v50 row_newbcast:2 row_mask:0xf bank_mask:0xf
	v_fmac_f32_dpp v121, v101, v51 row_newbcast:3 row_mask:0xf bank_mask:0xf
	v_fmac_f32_dpp v120, v101, v52 row_newbcast:4 row_mask:0xf bank_mask:0xf
	v_fmac_f32_dpp v121, v101, v53 row_newbcast:5 row_mask:0xf bank_mask:0xf
	v_fmac_f32_dpp v120, v101, v54 row_newbcast:6 row_mask:0xf bank_mask:0xf
	v_fmac_f32_dpp v121, v101, v55 row_newbcast:7 row_mask:0xf bank_mask:0xf
	v_fmac_f32_dpp v120, v101, v56 row_newbcast:8 row_mask:0xf bank_mask:0xf
	v_fmac_f32_dpp v121, v101, v57 row_newbcast:9 row_mask:0xf bank_mask:0xf
	v_fmac_f32_dpp v120, v101, v58 row_newbcast:10 row_mask:0xf bank_mask:0xf
	v_fmac_f32_dpp v121, v101, v59 row_newbcast:11 row_mask:0xf bank_mask:0xf
	v_fmac_f32_dpp v120, v101, v60 row_newbcast:12 row_mask:0xf bank_mask:0xf
	v_fmac_f32_dpp v121, v101, v61 row_newbcast:13 row_mask:0xf bank_mask:0xf
	v_fmac_f32_dpp v120, v101, v62 row_newbcast:14 row_mask:0xf bank_mask:0xf
	v_fmac_f32_dpp v121, v101, v63 row_newbcast:15 row_mask:0xf bank_mask:0xf
	v_add_f32_e32 v128, v120, v121
	s_nop 1
	v_permlane32_swap_b32 v129, v128
	s_nop 1
	v_add_f32_dpp v108, -v129, -v128 quad_perm:[0,1,2,3] row_mask:0xc bank_mask:0xf
	s_nop 1
	v_mfma_f32_32x32x2_f32 v[64:79], v104, v108, v[32:47]
	s_nop 15
	v_mfma_f32_32x32x2_f32 v[80:95], v105, v108, v[48:63]
	s_nop 7
	s_waitcnt lgkmcnt(0)
	ds_read_b32 v100, v14 offset:15616
	ds_read_b32 v101, v14 offset:15744
	ds_read_b32 v104, v15 offset:15360
	ds_read_b32 v105, v15 offset:15488
	ds_read_b32 v108, v16 offset:15360
	ds_read_b32 v114, v14 offset:16384
	ds_read_b32 v115, v14 offset:16512
	v_mul_f32_dpp v120, v102, v64 row_newbcast:0 row_mask:0xf bank_mask:0xf
	v_mul_f32_dpp v121, v102, v65 row_newbcast:1 row_mask:0xf bank_mask:0xf
	v_fmac_f32_dpp v120, v102, v66 row_newbcast:2 row_mask:0xf bank_mask:0xf
	v_fmac_f32_dpp v121, v102, v67 row_newbcast:3 row_mask:0xf bank_mask:0xf
	v_fmac_f32_dpp v120, v102, v68 row_newbcast:4 row_mask:0xf bank_mask:0xf
	v_fmac_f32_dpp v121, v102, v69 row_newbcast:5 row_mask:0xf bank_mask:0xf
	v_fmac_f32_dpp v120, v102, v70 row_newbcast:6 row_mask:0xf bank_mask:0xf
	v_fmac_f32_dpp v121, v102, v71 row_newbcast:7 row_mask:0xf bank_mask:0xf
	v_fmac_f32_dpp v120, v102, v72 row_newbcast:8 row_mask:0xf bank_mask:0xf
	v_fmac_f32_dpp v121, v102, v73 row_newbcast:9 row_mask:0xf bank_mask:0xf
	v_fmac_f32_dpp v120, v102, v74 row_newbcast:10 row_mask:0xf bank_mask:0xf
	v_fmac_f32_dpp v121, v102, v75 row_newbcast:11 row_mask:0xf bank_mask:0xf
	v_fmac_f32_dpp v120, v102, v76 row_newbcast:12 row_mask:0xf bank_mask:0xf
	v_fmac_f32_dpp v121, v102, v77 row_newbcast:13 row_mask:0xf bank_mask:0xf
	v_fmac_f32_dpp v120, v102, v78 row_newbcast:14 row_mask:0xf bank_mask:0xf
	v_fmac_f32_dpp v121, v102, v79 row_newbcast:15 row_mask:0xf bank_mask:0xf
	v_fmac_f32_dpp v120, v103, v80 row_newbcast:0 row_mask:0xf bank_mask:0xf
	v_fmac_f32_dpp v121, v103, v81 row_newbcast:1 row_mask:0xf bank_mask:0xf
	v_fmac_f32_dpp v120, v103, v82 row_newbcast:2 row_mask:0xf bank_mask:0xf
	v_fmac_f32_dpp v121, v103, v83 row_newbcast:3 row_mask:0xf bank_mask:0xf
	v_fmac_f32_dpp v120, v103, v84 row_newbcast:4 row_mask:0xf bank_mask:0xf
	v_fmac_f32_dpp v121, v103, v85 row_newbcast:5 row_mask:0xf bank_mask:0xf
	v_fmac_f32_dpp v120, v103, v86 row_newbcast:6 row_mask:0xf bank_mask:0xf
	v_fmac_f32_dpp v121, v103, v87 row_newbcast:7 row_mask:0xf bank_mask:0xf
	v_fmac_f32_dpp v120, v103, v88 row_newbcast:8 row_mask:0xf bank_mask:0xf
	v_fmac_f32_dpp v121, v103, v89 row_newbcast:9 row_mask:0xf bank_mask:0xf
	v_fmac_f32_dpp v120, v103, v90 row_newbcast:10 row_mask:0xf bank_mask:0xf
	v_fmac_f32_dpp v121, v103, v91 row_newbcast:11 row_mask:0xf bank_mask:0xf
	v_fmac_f32_dpp v120, v103, v92 row_newbcast:12 row_mask:0xf bank_mask:0xf
	v_fmac_f32_dpp v121, v103, v93 row_newbcast:13 row_mask:0xf bank_mask:0xf
	v_fmac_f32_dpp v120, v103, v94 row_newbcast:14 row_mask:0xf bank_mask:0xf
	v_fmac_f32_dpp v121, v103, v95 row_newbcast:15 row_mask:0xf bank_mask:0xf
	v_add_f32_e32 v128, v120, v121
	v_mul_f32_dpp v124, v110, v64 row_newbcast:0 row_mask:0xf bank_mask:0xf
	v_mul_f32_dpp v125, v110, v65 row_newbcast:1 row_mask:0xf bank_mask:0xf
	v_permlane32_swap_b32 v129, v128
	v_fmac_f32_dpp v124, v110, v66 row_newbcast:2 row_mask:0xf bank_mask:0xf
	v_fmac_f32_dpp v125, v110, v67 row_newbcast:3 row_mask:0xf bank_mask:0xf
	v_add_f32_dpp v109, -v129, -v128 quad_perm:[0,1,2,3] row_mask:0xc bank_mask:0xf
	v_fmac_f32_dpp v124, v110, v68 row_newbcast:4 row_mask:0xf bank_mask:0xf
	v_fmac_f32_dpp v125, v110, v69 row_newbcast:5 row_mask:0xf bank_mask:0xf
	v_mfma_f32_32x32x2_f32 v[32:47], v106, v109, v[64:79]
	v_fmac_f32_dpp v124, v110, v70 row_newbcast:6 row_mask:0xf bank_mask:0xf
	v_fmac_f32_dpp v125, v110, v71 row_newbcast:7 row_mask:0xf bank_mask:0xf
	v_fmac_f32_dpp v124, v110, v72 row_newbcast:8 row_mask:0xf bank_mask:0xf
	v_fmac_f32_dpp v125, v110, v73 row_newbcast:9 row_mask:0xf bank_mask:0xf
	v_fmac_f32_dpp v124, v110, v74 row_newbcast:10 row_mask:0xf bank_mask:0xf
	v_fmac_f32_dpp v125, v110, v75 row_newbcast:11 row_mask:0xf bank_mask:0xf
	v_fmac_f32_dpp v124, v110, v76 row_newbcast:12 row_mask:0xf bank_mask:0xf
	v_fmac_f32_dpp v125, v110, v77 row_newbcast:13 row_mask:0xf bank_mask:0xf
	v_fmac_f32_dpp v124, v110, v78 row_newbcast:14 row_mask:0xf bank_mask:0xf
	v_fmac_f32_dpp v125, v110, v79 row_newbcast:15 row_mask:0xf bank_mask:0xf
	v_fmac_f32_dpp v124, v111, v80 row_newbcast:0 row_mask:0xf bank_mask:0xf
	v_fmac_f32_dpp v125, v111, v81 row_newbcast:1 row_mask:0xf bank_mask:0xf
	v_fmac_f32_dpp v124, v111, v82 row_newbcast:2 row_mask:0xf bank_mask:0xf
	v_fmac_f32_dpp v125, v111, v83 row_newbcast:3 row_mask:0xf bank_mask:0xf
	v_mfma_f32_32x32x2_f32 v[48:63], v107, v109, v[80:95]
	v_fmac_f32_dpp v124, v111, v84 row_newbcast:4 row_mask:0xf bank_mask:0xf
	v_fmac_f32_dpp v125, v111, v85 row_newbcast:5 row_mask:0xf bank_mask:0xf
	v_fmac_f32_dpp v124, v111, v86 row_newbcast:6 row_mask:0xf bank_mask:0xf
	v_fmac_f32_dpp v125, v111, v87 row_newbcast:7 row_mask:0xf bank_mask:0xf
	v_fmac_f32_dpp v124, v111, v88 row_newbcast:8 row_mask:0xf bank_mask:0xf
	v_fmac_f32_dpp v125, v111, v89 row_newbcast:9 row_mask:0xf bank_mask:0xf
	v_fmac_f32_dpp v124, v111, v90 row_newbcast:10 row_mask:0xf bank_mask:0xf
	v_fmac_f32_dpp v125, v111, v91 row_newbcast:11 row_mask:0xf bank_mask:0xf
	v_fmac_f32_dpp v124, v111, v92 row_newbcast:12 row_mask:0xf bank_mask:0xf
	v_fmac_f32_dpp v125, v111, v93 row_newbcast:13 row_mask:0xf bank_mask:0xf
	v_fmac_f32_dpp v124, v111, v94 row_newbcast:14 row_mask:0xf bank_mask:0xf
	v_fmac_f32_dpp v125, v111, v95 row_newbcast:15 row_mask:0xf bank_mask:0xf
	v_add_f32_e32 v130, v124, v125
	s_waitcnt lgkmcnt(0)
	ds_read_b32 v102, v14 offset:17152
	ds_read_b32 v103, v14 offset:17280
	ds_read_b32 v106, v15 offset:16896
	ds_read_b32 v107, v15 offset:17024
	ds_read_b32 v109, v16 offset:16896
	ds_read_b32 v116, v14 offset:17920
	ds_read_b32 v117, v14 offset:18048
	v_mul_f32_dpp v120, v100, v32 row_newbcast:0 row_mask:0xf bank_mask:0xf
	v_mul_f32_dpp v121, v100, v33 row_newbcast:1 row_mask:0xf bank_mask:0xf
	v_fmac_f32_dpp v120, v100, v34 row_newbcast:2 row_mask:0xf bank_mask:0xf
	v_fmac_f32_dpp v121, v100, v35 row_newbcast:3 row_mask:0xf bank_mask:0xf
	v_fmac_f32_dpp v120, v100, v36 row_newbcast:4 row_mask:0xf bank_mask:0xf
	v_fmac_f32_dpp v121, v100, v37 row_newbcast:5 row_mask:0xf bank_mask:0xf
	v_fmac_f32_dpp v120, v100, v38 row_newbcast:6 row_mask:0xf bank_mask:0xf
	v_fmac_f32_dpp v121, v100, v39 row_newbcast:7 row_mask:0xf bank_mask:0xf
	v_fmac_f32_dpp v120, v100, v40 row_newbcast:8 row_mask:0xf bank_mask:0xf
	v_fmac_f32_dpp v121, v100, v41 row_newbcast:9 row_mask:0xf bank_mask:0xf
	v_fmac_f32_dpp v120, v100, v42 row_newbcast:10 row_mask:0xf bank_mask:0xf
	v_fmac_f32_dpp v121, v100, v43 row_newbcast:11 row_mask:0xf bank_mask:0xf
	v_fmac_f32_dpp v120, v100, v44 row_newbcast:12 row_mask:0xf bank_mask:0xf
	v_fmac_f32_dpp v121, v100, v45 row_newbcast:13 row_mask:0xf bank_mask:0xf
	v_fmac_f32_dpp v120, v100, v46 row_newbcast:14 row_mask:0xf bank_mask:0xf
	v_fmac_f32_dpp v121, v100, v47 row_newbcast:15 row_mask:0xf bank_mask:0xf
	v_fmac_f32_dpp v120, v101, v48 row_newbcast:0 row_mask:0xf bank_mask:0xf
	v_fmac_f32_dpp v121, v101, v49 row_newbcast:1 row_mask:0xf bank_mask:0xf
	v_fmac_f32_dpp v120, v101, v50 row_newbcast:2 row_mask:0xf bank_mask:0xf
	v_fmac_f32_dpp v121, v101, v51 row_newbcast:3 row_mask:0xf bank_mask:0xf
	v_fmac_f32_dpp v120, v101, v52 row_newbcast:4 row_mask:0xf bank_mask:0xf
	v_fmac_f32_dpp v121, v101, v53 row_newbcast:5 row_mask:0xf bank_mask:0xf
	v_fmac_f32_dpp v120, v101, v54 row_newbcast:6 row_mask:0xf bank_mask:0xf
	v_fmac_f32_dpp v121, v101, v55 row_newbcast:7 row_mask:0xf bank_mask:0xf
	v_fmac_f32_dpp v120, v101, v56 row_newbcast:8 row_mask:0xf bank_mask:0xf
	v_fmac_f32_dpp v121, v101, v57 row_newbcast:9 row_mask:0xf bank_mask:0xf
	v_fmac_f32_dpp v120, v101, v58 row_newbcast:10 row_mask:0xf bank_mask:0xf
	v_fmac_f32_dpp v121, v101, v59 row_newbcast:11 row_mask:0xf bank_mask:0xf
	v_fmac_f32_dpp v120, v101, v60 row_newbcast:12 row_mask:0xf bank_mask:0xf
	v_fmac_f32_dpp v121, v101, v61 row_newbcast:13 row_mask:0xf bank_mask:0xf
	v_fmac_f32_dpp v120, v101, v62 row_newbcast:14 row_mask:0xf bank_mask:0xf
	v_fmac_f32_dpp v121, v101, v63 row_newbcast:15 row_mask:0xf bank_mask:0xf
	v_add_f32_e32 v128, v120, v121
	v_mul_f32_dpp v124, v112, v32 row_newbcast:0 row_mask:0xf bank_mask:0xf
	v_mul_f32_dpp v125, v112, v33 row_newbcast:1 row_mask:0xf bank_mask:0xf
	v_permlane32_swap_b32 v129, v128
	v_fmac_f32_dpp v124, v112, v34 row_newbcast:2 row_mask:0xf bank_mask:0xf
	v_fmac_f32_dpp v125, v112, v35 row_newbcast:3 row_mask:0xf bank_mask:0xf
	v_add_f32_dpp v108, -v129, -v128 quad_perm:[0,1,2,3] row_mask:0xc bank_mask:0xf
	v_fmac_f32_dpp v124, v112, v36 row_newbcast:4 row_mask:0xf bank_mask:0xf
	v_fmac_f32_dpp v125, v112, v37 row_newbcast:5 row_mask:0xf bank_mask:0xf
	v_mfma_f32_32x32x2_f32 v[64:79], v104, v108, v[32:47]
	v_fmac_f32_dpp v124, v112, v38 row_newbcast:6 row_mask:0xf bank_mask:0xf
	v_fmac_f32_dpp v125, v112, v39 row_newbcast:7 row_mask:0xf bank_mask:0xf
	v_fmac_f32_dpp v124, v112, v40 row_newbcast:8 row_mask:0xf bank_mask:0xf
	v_fmac_f32_dpp v125, v112, v41 row_newbcast:9 row_mask:0xf bank_mask:0xf
	v_fmac_f32_dpp v124, v112, v42 row_newbcast:10 row_mask:0xf bank_mask:0xf
	v_fmac_f32_dpp v125, v112, v43 row_newbcast:11 row_mask:0xf bank_mask:0xf
	v_fmac_f32_dpp v124, v112, v44 row_newbcast:12 row_mask:0xf bank_mask:0xf
	v_fmac_f32_dpp v125, v112, v45 row_newbcast:13 row_mask:0xf bank_mask:0xf
	v_fmac_f32_dpp v124, v112, v46 row_newbcast:14 row_mask:0xf bank_mask:0xf
	v_fmac_f32_dpp v125, v112, v47 row_newbcast:15 row_mask:0xf bank_mask:0xf
	v_fmac_f32_dpp v124, v113, v48 row_newbcast:0 row_mask:0xf bank_mask:0xf
	v_fmac_f32_dpp v125, v113, v49 row_newbcast:1 row_mask:0xf bank_mask:0xf
	v_fmac_f32_dpp v124, v113, v50 row_newbcast:2 row_mask:0xf bank_mask:0xf
	v_fmac_f32_dpp v125, v113, v51 row_newbcast:3 row_mask:0xf bank_mask:0xf
	v_mfma_f32_32x32x2_f32 v[80:95], v105, v108, v[48:63]
	v_fmac_f32_dpp v124, v113, v52 row_newbcast:4 row_mask:0xf bank_mask:0xf
	v_fmac_f32_dpp v125, v113, v53 row_newbcast:5 row_mask:0xf bank_mask:0xf
	v_fmac_f32_dpp v124, v113, v54 row_newbcast:6 row_mask:0xf bank_mask:0xf
	v_fmac_f32_dpp v125, v113, v55 row_newbcast:7 row_mask:0xf bank_mask:0xf
	v_fmac_f32_dpp v124, v113, v56 row_newbcast:8 row_mask:0xf bank_mask:0xf
	v_fmac_f32_dpp v125, v113, v57 row_newbcast:9 row_mask:0xf bank_mask:0xf
	v_fmac_f32_dpp v124, v113, v58 row_newbcast:10 row_mask:0xf bank_mask:0xf
	v_fmac_f32_dpp v125, v113, v59 row_newbcast:11 row_mask:0xf bank_mask:0xf
	v_fmac_f32_dpp v124, v113, v60 row_newbcast:12 row_mask:0xf bank_mask:0xf
	v_fmac_f32_dpp v125, v113, v61 row_newbcast:13 row_mask:0xf bank_mask:0xf
	v_fmac_f32_dpp v124, v113, v62 row_newbcast:14 row_mask:0xf bank_mask:0xf
	v_fmac_f32_dpp v125, v113, v63 row_newbcast:15 row_mask:0xf bank_mask:0xf
	v_add_f32_e32 v131, v124, v125
	s_nop 1
	v_permlane32_swap_b32 v130, v131
	v_add_f32_e32 v133, v130, v131
	v_cvt_pk_bf16_f32 v133, v133, v133
	global_store_short v13, v133, s[16:17]
	s_add_u32 s16, s16, s20
	s_addc_u32 s17, s17, s21
	s_waitcnt lgkmcnt(0)
	ds_read_b32 v100, v14 offset:18688
	ds_read_b32 v101, v14 offset:18816
	ds_read_b32 v104, v15 offset:18432
	ds_read_b32 v105, v15 offset:18560
	ds_read_b32 v108, v16 offset:18432
	ds_read_b32 v110, v14 offset:19456
	ds_read_b32 v111, v14 offset:19584
	v_mul_f32_dpp v120, v102, v64 row_newbcast:0 row_mask:0xf bank_mask:0xf
	v_mul_f32_dpp v121, v102, v65 row_newbcast:1 row_mask:0xf bank_mask:0xf
	v_fmac_f32_dpp v120, v102, v66 row_newbcast:2 row_mask:0xf bank_mask:0xf
	v_fmac_f32_dpp v121, v102, v67 row_newbcast:3 row_mask:0xf bank_mask:0xf
	v_fmac_f32_dpp v120, v102, v68 row_newbcast:4 row_mask:0xf bank_mask:0xf
	v_fmac_f32_dpp v121, v102, v69 row_newbcast:5 row_mask:0xf bank_mask:0xf
	v_fmac_f32_dpp v120, v102, v70 row_newbcast:6 row_mask:0xf bank_mask:0xf
	v_fmac_f32_dpp v121, v102, v71 row_newbcast:7 row_mask:0xf bank_mask:0xf
	v_fmac_f32_dpp v120, v102, v72 row_newbcast:8 row_mask:0xf bank_mask:0xf
	v_fmac_f32_dpp v121, v102, v73 row_newbcast:9 row_mask:0xf bank_mask:0xf
	v_fmac_f32_dpp v120, v102, v74 row_newbcast:10 row_mask:0xf bank_mask:0xf
	v_fmac_f32_dpp v121, v102, v75 row_newbcast:11 row_mask:0xf bank_mask:0xf
	v_fmac_f32_dpp v120, v102, v76 row_newbcast:12 row_mask:0xf bank_mask:0xf
	v_fmac_f32_dpp v121, v102, v77 row_newbcast:13 row_mask:0xf bank_mask:0xf
	v_fmac_f32_dpp v120, v102, v78 row_newbcast:14 row_mask:0xf bank_mask:0xf
	v_fmac_f32_dpp v121, v102, v79 row_newbcast:15 row_mask:0xf bank_mask:0xf
	v_fmac_f32_dpp v120, v103, v80 row_newbcast:0 row_mask:0xf bank_mask:0xf
	v_fmac_f32_dpp v121, v103, v81 row_newbcast:1 row_mask:0xf bank_mask:0xf
	v_fmac_f32_dpp v120, v103, v82 row_newbcast:2 row_mask:0xf bank_mask:0xf
	v_fmac_f32_dpp v121, v103, v83 row_newbcast:3 row_mask:0xf bank_mask:0xf
	v_fmac_f32_dpp v120, v103, v84 row_newbcast:4 row_mask:0xf bank_mask:0xf
	v_fmac_f32_dpp v121, v103, v85 row_newbcast:5 row_mask:0xf bank_mask:0xf
	v_fmac_f32_dpp v120, v103, v86 row_newbcast:6 row_mask:0xf bank_mask:0xf
	v_fmac_f32_dpp v121, v103, v87 row_newbcast:7 row_mask:0xf bank_mask:0xf
	v_fmac_f32_dpp v120, v103, v88 row_newbcast:8 row_mask:0xf bank_mask:0xf
	v_fmac_f32_dpp v121, v103, v89 row_newbcast:9 row_mask:0xf bank_mask:0xf
	v_fmac_f32_dpp v120, v103, v90 row_newbcast:10 row_mask:0xf bank_mask:0xf
	v_fmac_f32_dpp v121, v103, v91 row_newbcast:11 row_mask:0xf bank_mask:0xf
	v_fmac_f32_dpp v120, v103, v92 row_newbcast:12 row_mask:0xf bank_mask:0xf
	v_fmac_f32_dpp v121, v103, v93 row_newbcast:13 row_mask:0xf bank_mask:0xf
	v_fmac_f32_dpp v120, v103, v94 row_newbcast:14 row_mask:0xf bank_mask:0xf
	v_fmac_f32_dpp v121, v103, v95 row_newbcast:15 row_mask:0xf bank_mask:0xf
	v_add_f32_e32 v128, v120, v121
	v_mul_f32_dpp v124, v114, v64 row_newbcast:0 row_mask:0xf bank_mask:0xf
	v_mul_f32_dpp v125, v114, v65 row_newbcast:1 row_mask:0xf bank_mask:0xf
	v_permlane32_swap_b32 v129, v128
	v_fmac_f32_dpp v124, v114, v66 row_newbcast:2 row_mask:0xf bank_mask:0xf
	v_fmac_f32_dpp v125, v114, v67 row_newbcast:3 row_mask:0xf bank_mask:0xf
	v_add_f32_dpp v109, -v129, -v128 quad_perm:[0,1,2,3] row_mask:0xc bank_mask:0xf
	v_fmac_f32_dpp v124, v114, v68 row_newbcast:4 row_mask:0xf bank_mask:0xf
	v_fmac_f32_dpp v125, v114, v69 row_newbcast:5 row_mask:0xf bank_mask:0xf
	v_mfma_f32_32x32x2_f32 v[32:47], v106, v109, v[64:79]
	v_fmac_f32_dpp v124, v114, v70 row_newbcast:6 row_mask:0xf bank_mask:0xf
	v_fmac_f32_dpp v125, v114, v71 row_newbcast:7 row_mask:0xf bank_mask:0xf
	v_fmac_f32_dpp v124, v114, v72 row_newbcast:8 row_mask:0xf bank_mask:0xf
	v_fmac_f32_dpp v125, v114, v73 row_newbcast:9 row_mask:0xf bank_mask:0xf
	v_fmac_f32_dpp v124, v114, v74 row_newbcast:10 row_mask:0xf bank_mask:0xf
	v_fmac_f32_dpp v125, v114, v75 row_newbcast:11 row_mask:0xf bank_mask:0xf
	v_fmac_f32_dpp v124, v114, v76 row_newbcast:12 row_mask:0xf bank_mask:0xf
	v_fmac_f32_dpp v125, v114, v77 row_newbcast:13 row_mask:0xf bank_mask:0xf
	v_fmac_f32_dpp v124, v114, v78 row_newbcast:14 row_mask:0xf bank_mask:0xf
	v_fmac_f32_dpp v125, v114, v79 row_newbcast:15 row_mask:0xf bank_mask:0xf
	v_fmac_f32_dpp v124, v115, v80 row_newbcast:0 row_mask:0xf bank_mask:0xf
	v_fmac_f32_dpp v125, v115, v81 row_newbcast:1 row_mask:0xf bank_mask:0xf
	v_fmac_f32_dpp v124, v115, v82 row_newbcast:2 row_mask:0xf bank_mask:0xf
	v_fmac_f32_dpp v125, v115, v83 row_newbcast:3 row_mask:0xf bank_mask:0xf
	v_mfma_f32_32x32x2_f32 v[48:63], v107, v109, v[80:95]
	v_fmac_f32_dpp v124, v115, v84 row_newbcast:4 row_mask:0xf bank_mask:0xf
	v_fmac_f32_dpp v125, v115, v85 row_newbcast:5 row_mask:0xf bank_mask:0xf
	v_fmac_f32_dpp v124, v115, v86 row_newbcast:6 row_mask:0xf bank_mask:0xf
	v_fmac_f32_dpp v125, v115, v87 row_newbcast:7 row_mask:0xf bank_mask:0xf
	v_fmac_f32_dpp v124, v115, v88 row_newbcast:8 row_mask:0xf bank_mask:0xf
	v_fmac_f32_dpp v125, v115, v89 row_newbcast:9 row_mask:0xf bank_mask:0xf
	v_fmac_f32_dpp v124, v115, v90 row_newbcast:10 row_mask:0xf bank_mask:0xf
	v_fmac_f32_dpp v125, v115, v91 row_newbcast:11 row_mask:0xf bank_mask:0xf
	v_fmac_f32_dpp v124, v115, v92 row_newbcast:12 row_mask:0xf bank_mask:0xf
	v_fmac_f32_dpp v125, v115, v93 row_newbcast:13 row_mask:0xf bank_mask:0xf
	v_fmac_f32_dpp v124, v115, v94 row_newbcast:14 row_mask:0xf bank_mask:0xf
	v_fmac_f32_dpp v125, v115, v95 row_newbcast:15 row_mask:0xf bank_mask:0xf
	v_add_f32_e32 v130, v124, v125
	s_waitcnt lgkmcnt(0)
	ds_read_b32 v102, v14 offset:20224
	ds_read_b32 v103, v14 offset:20352
	ds_read_b32 v106, v15 offset:19968
	ds_read_b32 v107, v15 offset:20096
	ds_read_b32 v109, v16 offset:19968
	ds_read_b32 v112, v14 offset:20992
	ds_read_b32 v113, v14 offset:21120
	v_mul_f32_dpp v120, v100, v32 row_newbcast:0 row_mask:0xf bank_mask:0xf
	v_mul_f32_dpp v121, v100, v33 row_newbcast:1 row_mask:0xf bank_mask:0xf
	v_fmac_f32_dpp v120, v100, v34 row_newbcast:2 row_mask:0xf bank_mask:0xf
	v_fmac_f32_dpp v121, v100, v35 row_newbcast:3 row_mask:0xf bank_mask:0xf
	v_fmac_f32_dpp v120, v100, v36 row_newbcast:4 row_mask:0xf bank_mask:0xf
	v_fmac_f32_dpp v121, v100, v37 row_newbcast:5 row_mask:0xf bank_mask:0xf
	v_fmac_f32_dpp v120, v100, v38 row_newbcast:6 row_mask:0xf bank_mask:0xf
	v_fmac_f32_dpp v121, v100, v39 row_newbcast:7 row_mask:0xf bank_mask:0xf
	v_fmac_f32_dpp v120, v100, v40 row_newbcast:8 row_mask:0xf bank_mask:0xf
	v_fmac_f32_dpp v121, v100, v41 row_newbcast:9 row_mask:0xf bank_mask:0xf
	v_fmac_f32_dpp v120, v100, v42 row_newbcast:10 row_mask:0xf bank_mask:0xf
	v_fmac_f32_dpp v121, v100, v43 row_newbcast:11 row_mask:0xf bank_mask:0xf
	v_fmac_f32_dpp v120, v100, v44 row_newbcast:12 row_mask:0xf bank_mask:0xf
	v_fmac_f32_dpp v121, v100, v45 row_newbcast:13 row_mask:0xf bank_mask:0xf
	v_fmac_f32_dpp v120, v100, v46 row_newbcast:14 row_mask:0xf bank_mask:0xf
	v_fmac_f32_dpp v121, v100, v47 row_newbcast:15 row_mask:0xf bank_mask:0xf
	v_fmac_f32_dpp v120, v101, v48 row_newbcast:0 row_mask:0xf bank_mask:0xf
	v_fmac_f32_dpp v121, v101, v49 row_newbcast:1 row_mask:0xf bank_mask:0xf
	v_fmac_f32_dpp v120, v101, v50 row_newbcast:2 row_mask:0xf bank_mask:0xf
	v_fmac_f32_dpp v121, v101, v51 row_newbcast:3 row_mask:0xf bank_mask:0xf
	v_fmac_f32_dpp v120, v101, v52 row_newbcast:4 row_mask:0xf bank_mask:0xf
	v_fmac_f32_dpp v121, v101, v53 row_newbcast:5 row_mask:0xf bank_mask:0xf
	v_fmac_f32_dpp v120, v101, v54 row_newbcast:6 row_mask:0xf bank_mask:0xf
	v_fmac_f32_dpp v121, v101, v55 row_newbcast:7 row_mask:0xf bank_mask:0xf
	v_fmac_f32_dpp v120, v101, v56 row_newbcast:8 row_mask:0xf bank_mask:0xf
	v_fmac_f32_dpp v121, v101, v57 row_newbcast:9 row_mask:0xf bank_mask:0xf
	v_fmac_f32_dpp v120, v101, v58 row_newbcast:10 row_mask:0xf bank_mask:0xf
	v_fmac_f32_dpp v121, v101, v59 row_newbcast:11 row_mask:0xf bank_mask:0xf
	v_fmac_f32_dpp v120, v101, v60 row_newbcast:12 row_mask:0xf bank_mask:0xf
	v_fmac_f32_dpp v121, v101, v61 row_newbcast:13 row_mask:0xf bank_mask:0xf
	v_fmac_f32_dpp v120, v101, v62 row_newbcast:14 row_mask:0xf bank_mask:0xf
	v_fmac_f32_dpp v121, v101, v63 row_newbcast:15 row_mask:0xf bank_mask:0xf
	v_add_f32_e32 v128, v120, v121
	v_mul_f32_dpp v124, v116, v32 row_newbcast:0 row_mask:0xf bank_mask:0xf
	v_mul_f32_dpp v125, v116, v33 row_newbcast:1 row_mask:0xf bank_mask:0xf
	v_permlane32_swap_b32 v129, v128
	v_fmac_f32_dpp v124, v116, v34 row_newbcast:2 row_mask:0xf bank_mask:0xf
	v_fmac_f32_dpp v125, v116, v35 row_newbcast:3 row_mask:0xf bank_mask:0xf
	v_add_f32_dpp v108, -v129, -v128 quad_perm:[0,1,2,3] row_mask:0xc bank_mask:0xf
	v_fmac_f32_dpp v124, v116, v36 row_newbcast:4 row_mask:0xf bank_mask:0xf
	v_fmac_f32_dpp v125, v116, v37 row_newbcast:5 row_mask:0xf bank_mask:0xf
	v_mfma_f32_32x32x2_f32 v[64:79], v104, v108, v[32:47]
	v_fmac_f32_dpp v124, v116, v38 row_newbcast:6 row_mask:0xf bank_mask:0xf
	v_fmac_f32_dpp v125, v116, v39 row_newbcast:7 row_mask:0xf bank_mask:0xf
	v_fmac_f32_dpp v124, v116, v40 row_newbcast:8 row_mask:0xf bank_mask:0xf
	v_fmac_f32_dpp v125, v116, v41 row_newbcast:9 row_mask:0xf bank_mask:0xf
	v_fmac_f32_dpp v124, v116, v42 row_newbcast:10 row_mask:0xf bank_mask:0xf
	v_fmac_f32_dpp v125, v116, v43 row_newbcast:11 row_mask:0xf bank_mask:0xf
	v_fmac_f32_dpp v124, v116, v44 row_newbcast:12 row_mask:0xf bank_mask:0xf
	v_fmac_f32_dpp v125, v116, v45 row_newbcast:13 row_mask:0xf bank_mask:0xf
	v_fmac_f32_dpp v124, v116, v46 row_newbcast:14 row_mask:0xf bank_mask:0xf
	v_fmac_f32_dpp v125, v116, v47 row_newbcast:15 row_mask:0xf bank_mask:0xf
	v_fmac_f32_dpp v124, v117, v48 row_newbcast:0 row_mask:0xf bank_mask:0xf
	v_fmac_f32_dpp v125, v117, v49 row_newbcast:1 row_mask:0xf bank_mask:0xf
	v_fmac_f32_dpp v124, v117, v50 row_newbcast:2 row_mask:0xf bank_mask:0xf
	v_fmac_f32_dpp v125, v117, v51 row_newbcast:3 row_mask:0xf bank_mask:0xf
	v_mfma_f32_32x32x2_f32 v[80:95], v105, v108, v[48:63]
	v_fmac_f32_dpp v124, v117, v52 row_newbcast:4 row_mask:0xf bank_mask:0xf
	v_fmac_f32_dpp v125, v117, v53 row_newbcast:5 row_mask:0xf bank_mask:0xf
	v_fmac_f32_dpp v124, v117, v54 row_newbcast:6 row_mask:0xf bank_mask:0xf
	v_fmac_f32_dpp v125, v117, v55 row_newbcast:7 row_mask:0xf bank_mask:0xf
	v_fmac_f32_dpp v124, v117, v56 row_newbcast:8 row_mask:0xf bank_mask:0xf
	v_fmac_f32_dpp v125, v117, v57 row_newbcast:9 row_mask:0xf bank_mask:0xf
	v_fmac_f32_dpp v124, v117, v58 row_newbcast:10 row_mask:0xf bank_mask:0xf
	v_fmac_f32_dpp v125, v117, v59 row_newbcast:11 row_mask:0xf bank_mask:0xf
	v_fmac_f32_dpp v124, v117, v60 row_newbcast:12 row_mask:0xf bank_mask:0xf
	v_fmac_f32_dpp v125, v117, v61 row_newbcast:13 row_mask:0xf bank_mask:0xf
	v_fmac_f32_dpp v124, v117, v62 row_newbcast:14 row_mask:0xf bank_mask:0xf
	v_fmac_f32_dpp v125, v117, v63 row_newbcast:15 row_mask:0xf bank_mask:0xf
	v_add_f32_e32 v131, v124, v125
	s_nop 1
	v_permlane32_swap_b32 v130, v131
	v_add_f32_e32 v133, v130, v131
	v_cvt_pk_bf16_f32 v133, v133, v133
	global_store_short v13, v133, s[16:17]
	s_add_u32 s16, s16, s20
	s_addc_u32 s17, s17, s21
	s_waitcnt lgkmcnt(0)
	ds_read_b32 v100, v14 offset:21760
	ds_read_b32 v101, v14 offset:21888
	ds_read_b32 v104, v15 offset:21504
	ds_read_b32 v105, v15 offset:21632
	ds_read_b32 v108, v16 offset:21504
	ds_read_b32 v114, v14 offset:22528
	ds_read_b32 v115, v14 offset:22656
	v_mul_f32_dpp v120, v102, v64 row_newbcast:0 row_mask:0xf bank_mask:0xf
	v_mul_f32_dpp v121, v102, v65 row_newbcast:1 row_mask:0xf bank_mask:0xf
	v_fmac_f32_dpp v120, v102, v66 row_newbcast:2 row_mask:0xf bank_mask:0xf
	v_fmac_f32_dpp v121, v102, v67 row_newbcast:3 row_mask:0xf bank_mask:0xf
	v_fmac_f32_dpp v120, v102, v68 row_newbcast:4 row_mask:0xf bank_mask:0xf
	v_fmac_f32_dpp v121, v102, v69 row_newbcast:5 row_mask:0xf bank_mask:0xf
	v_fmac_f32_dpp v120, v102, v70 row_newbcast:6 row_mask:0xf bank_mask:0xf
	v_fmac_f32_dpp v121, v102, v71 row_newbcast:7 row_mask:0xf bank_mask:0xf
	v_fmac_f32_dpp v120, v102, v72 row_newbcast:8 row_mask:0xf bank_mask:0xf
	v_fmac_f32_dpp v121, v102, v73 row_newbcast:9 row_mask:0xf bank_mask:0xf
	v_fmac_f32_dpp v120, v102, v74 row_newbcast:10 row_mask:0xf bank_mask:0xf
	v_fmac_f32_dpp v121, v102, v75 row_newbcast:11 row_mask:0xf bank_mask:0xf
	v_fmac_f32_dpp v120, v102, v76 row_newbcast:12 row_mask:0xf bank_mask:0xf
	v_fmac_f32_dpp v121, v102, v77 row_newbcast:13 row_mask:0xf bank_mask:0xf
	v_fmac_f32_dpp v120, v102, v78 row_newbcast:14 row_mask:0xf bank_mask:0xf
	v_fmac_f32_dpp v121, v102, v79 row_newbcast:15 row_mask:0xf bank_mask:0xf
	v_fmac_f32_dpp v120, v103, v80 row_newbcast:0 row_mask:0xf bank_mask:0xf
	v_fmac_f32_dpp v121, v103, v81 row_newbcast:1 row_mask:0xf bank_mask:0xf
	v_fmac_f32_dpp v120, v103, v82 row_newbcast:2 row_mask:0xf bank_mask:0xf
	v_fmac_f32_dpp v121, v103, v83 row_newbcast:3 row_mask:0xf bank_mask:0xf
	v_fmac_f32_dpp v120, v103, v84 row_newbcast:4 row_mask:0xf bank_mask:0xf
	v_fmac_f32_dpp v121, v103, v85 row_newbcast:5 row_mask:0xf bank_mask:0xf
	v_fmac_f32_dpp v120, v103, v86 row_newbcast:6 row_mask:0xf bank_mask:0xf
	v_fmac_f32_dpp v121, v103, v87 row_newbcast:7 row_mask:0xf bank_mask:0xf
	v_fmac_f32_dpp v120, v103, v88 row_newbcast:8 row_mask:0xf bank_mask:0xf
	v_fmac_f32_dpp v121, v103, v89 row_newbcast:9 row_mask:0xf bank_mask:0xf
	v_fmac_f32_dpp v120, v103, v90 row_newbcast:10 row_mask:0xf bank_mask:0xf
	v_fmac_f32_dpp v121, v103, v91 row_newbcast:11 row_mask:0xf bank_mask:0xf
	v_fmac_f32_dpp v120, v103, v92 row_newbcast:12 row_mask:0xf bank_mask:0xf
	v_fmac_f32_dpp v121, v103, v93 row_newbcast:13 row_mask:0xf bank_mask:0xf
	v_fmac_f32_dpp v120, v103, v94 row_newbcast:14 row_mask:0xf bank_mask:0xf
	v_fmac_f32_dpp v121, v103, v95 row_newbcast:15 row_mask:0xf bank_mask:0xf
	v_add_f32_e32 v128, v120, v121
	v_mul_f32_dpp v124, v110, v64 row_newbcast:0 row_mask:0xf bank_mask:0xf
	v_mul_f32_dpp v125, v110, v65 row_newbcast:1 row_mask:0xf bank_mask:0xf
	v_permlane32_swap_b32 v129, v128
	v_fmac_f32_dpp v124, v110, v66 row_newbcast:2 row_mask:0xf bank_mask:0xf
	v_fmac_f32_dpp v125, v110, v67 row_newbcast:3 row_mask:0xf bank_mask:0xf
	v_add_f32_dpp v109, -v129, -v128 quad_perm:[0,1,2,3] row_mask:0xc bank_mask:0xf
	v_fmac_f32_dpp v124, v110, v68 row_newbcast:4 row_mask:0xf bank_mask:0xf
	v_fmac_f32_dpp v125, v110, v69 row_newbcast:5 row_mask:0xf bank_mask:0xf
	v_mfma_f32_32x32x2_f32 v[32:47], v106, v109, v[64:79]
	v_fmac_f32_dpp v124, v110, v70 row_newbcast:6 row_mask:0xf bank_mask:0xf
	v_fmac_f32_dpp v125, v110, v71 row_newbcast:7 row_mask:0xf bank_mask:0xf
	v_fmac_f32_dpp v124, v110, v72 row_newbcast:8 row_mask:0xf bank_mask:0xf
	v_fmac_f32_dpp v125, v110, v73 row_newbcast:9 row_mask:0xf bank_mask:0xf
	v_fmac_f32_dpp v124, v110, v74 row_newbcast:10 row_mask:0xf bank_mask:0xf
	v_fmac_f32_dpp v125, v110, v75 row_newbcast:11 row_mask:0xf bank_mask:0xf
	v_fmac_f32_dpp v124, v110, v76 row_newbcast:12 row_mask:0xf bank_mask:0xf
	v_fmac_f32_dpp v125, v110, v77 row_newbcast:13 row_mask:0xf bank_mask:0xf
	v_fmac_f32_dpp v124, v110, v78 row_newbcast:14 row_mask:0xf bank_mask:0xf
	v_fmac_f32_dpp v125, v110, v79 row_newbcast:15 row_mask:0xf bank_mask:0xf
	v_fmac_f32_dpp v124, v111, v80 row_newbcast:0 row_mask:0xf bank_mask:0xf
	v_fmac_f32_dpp v125, v111, v81 row_newbcast:1 row_mask:0xf bank_mask:0xf
	v_fmac_f32_dpp v124, v111, v82 row_newbcast:2 row_mask:0xf bank_mask:0xf
	v_fmac_f32_dpp v125, v111, v83 row_newbcast:3 row_mask:0xf bank_mask:0xf
	v_mfma_f32_32x32x2_f32 v[48:63], v107, v109, v[80:95]
	v_fmac_f32_dpp v124, v111, v84 row_newbcast:4 row_mask:0xf bank_mask:0xf
	v_fmac_f32_dpp v125, v111, v85 row_newbcast:5 row_mask:0xf bank_mask:0xf
	v_fmac_f32_dpp v124, v111, v86 row_newbcast:6 row_mask:0xf bank_mask:0xf
	v_fmac_f32_dpp v125, v111, v87 row_newbcast:7 row_mask:0xf bank_mask:0xf
	v_fmac_f32_dpp v124, v111, v88 row_newbcast:8 row_mask:0xf bank_mask:0xf
	v_fmac_f32_dpp v125, v111, v89 row_newbcast:9 row_mask:0xf bank_mask:0xf
	v_fmac_f32_dpp v124, v111, v90 row_newbcast:10 row_mask:0xf bank_mask:0xf
	v_fmac_f32_dpp v125, v111, v91 row_newbcast:11 row_mask:0xf bank_mask:0xf
	v_fmac_f32_dpp v124, v111, v92 row_newbcast:12 row_mask:0xf bank_mask:0xf
	v_fmac_f32_dpp v125, v111, v93 row_newbcast:13 row_mask:0xf bank_mask:0xf
	v_fmac_f32_dpp v124, v111, v94 row_newbcast:14 row_mask:0xf bank_mask:0xf
	v_fmac_f32_dpp v125, v111, v95 row_newbcast:15 row_mask:0xf bank_mask:0xf
	v_add_f32_e32 v130, v124, v125
	s_waitcnt lgkmcnt(0)
	ds_read_b32 v102, v14 offset:23296
	ds_read_b32 v103, v14 offset:23424
	ds_read_b32 v106, v15 offset:23040
	ds_read_b32 v107, v15 offset:23168
	ds_read_b32 v109, v16 offset:23040
	ds_read_b32 v116, v14 offset:24064
	ds_read_b32 v117, v14 offset:24192
	ds_read_b32 v118, v14 offset:23040
	ds_read_b32 v119, v14 offset:23168
	v_mul_f32_dpp v120, v100, v32 row_newbcast:0 row_mask:0xf bank_mask:0xf
	v_mul_f32_dpp v121, v100, v33 row_newbcast:1 row_mask:0xf bank_mask:0xf
	v_fmac_f32_dpp v120, v100, v34 row_newbcast:2 row_mask:0xf bank_mask:0xf
	v_fmac_f32_dpp v121, v100, v35 row_newbcast:3 row_mask:0xf bank_mask:0xf
	v_fmac_f32_dpp v120, v100, v36 row_newbcast:4 row_mask:0xf bank_mask:0xf
	v_fmac_f32_dpp v121, v100, v37 row_newbcast:5 row_mask:0xf bank_mask:0xf
	v_fmac_f32_dpp v120, v100, v38 row_newbcast:6 row_mask:0xf bank_mask:0xf
	v_fmac_f32_dpp v121, v100, v39 row_newbcast:7 row_mask:0xf bank_mask:0xf
	v_fmac_f32_dpp v120, v100, v40 row_newbcast:8 row_mask:0xf bank_mask:0xf
	v_fmac_f32_dpp v121, v100, v41 row_newbcast:9 row_mask:0xf bank_mask:0xf
	v_fmac_f32_dpp v120, v100, v42 row_newbcast:10 row_mask:0xf bank_mask:0xf
	v_fmac_f32_dpp v121, v100, v43 row_newbcast:11 row_mask:0xf bank_mask:0xf
	v_fmac_f32_dpp v120, v100, v44 row_newbcast:12 row_mask:0xf bank_mask:0xf
	v_fmac_f32_dpp v121, v100, v45 row_newbcast:13 row_mask:0xf bank_mask:0xf
	v_fmac_f32_dpp v120, v100, v46 row_newbcast:14 row_mask:0xf bank_mask:0xf
	v_fmac_f32_dpp v121, v100, v47 row_newbcast:15 row_mask:0xf bank_mask:0xf
	v_fmac_f32_dpp v120, v101, v48 row_newbcast:0 row_mask:0xf bank_mask:0xf
	v_fmac_f32_dpp v121, v101, v49 row_newbcast:1 row_mask:0xf bank_mask:0xf
	v_fmac_f32_dpp v120, v101, v50 row_newbcast:2 row_mask:0xf bank_mask:0xf
	v_fmac_f32_dpp v121, v101, v51 row_newbcast:3 row_mask:0xf bank_mask:0xf
	v_fmac_f32_dpp v120, v101, v52 row_newbcast:4 row_mask:0xf bank_mask:0xf
	v_fmac_f32_dpp v121, v101, v53 row_newbcast:5 row_mask:0xf bank_mask:0xf
	v_fmac_f32_dpp v120, v101, v54 row_newbcast:6 row_mask:0xf bank_mask:0xf
	v_fmac_f32_dpp v121, v101, v55 row_newbcast:7 row_mask:0xf bank_mask:0xf
	v_fmac_f32_dpp v120, v101, v56 row_newbcast:8 row_mask:0xf bank_mask:0xf
	v_fmac_f32_dpp v121, v101, v57 row_newbcast:9 row_mask:0xf bank_mask:0xf
	v_fmac_f32_dpp v120, v101, v58 row_newbcast:10 row_mask:0xf bank_mask:0xf
	v_fmac_f32_dpp v121, v101, v59 row_newbcast:11 row_mask:0xf bank_mask:0xf
	v_fmac_f32_dpp v120, v101, v60 row_newbcast:12 row_mask:0xf bank_mask:0xf
	v_fmac_f32_dpp v121, v101, v61 row_newbcast:13 row_mask:0xf bank_mask:0xf
	v_fmac_f32_dpp v120, v101, v62 row_newbcast:14 row_mask:0xf bank_mask:0xf
	v_fmac_f32_dpp v121, v101, v63 row_newbcast:15 row_mask:0xf bank_mask:0xf
	v_add_f32_e32 v128, v120, v121
	v_mul_f32_dpp v124, v112, v32 row_newbcast:0 row_mask:0xf bank_mask:0xf
	v_mul_f32_dpp v125, v112, v33 row_newbcast:1 row_mask:0xf bank_mask:0xf
	v_permlane32_swap_b32 v129, v128
	v_fmac_f32_dpp v124, v112, v34 row_newbcast:2 row_mask:0xf bank_mask:0xf
	v_fmac_f32_dpp v125, v112, v35 row_newbcast:3 row_mask:0xf bank_mask:0xf
	v_add_f32_dpp v108, -v129, -v128 quad_perm:[0,1,2,3] row_mask:0xc bank_mask:0xf
	v_fmac_f32_dpp v124, v112, v36 row_newbcast:4 row_mask:0xf bank_mask:0xf
	v_fmac_f32_dpp v125, v112, v37 row_newbcast:5 row_mask:0xf bank_mask:0xf
	v_mfma_f32_32x32x2_f32 v[64:79], v104, v108, v[32:47]
	v_fmac_f32_dpp v124, v112, v38 row_newbcast:6 row_mask:0xf bank_mask:0xf
	v_fmac_f32_dpp v125, v112, v39 row_newbcast:7 row_mask:0xf bank_mask:0xf
	v_fmac_f32_dpp v124, v112, v40 row_newbcast:8 row_mask:0xf bank_mask:0xf
	v_fmac_f32_dpp v125, v112, v41 row_newbcast:9 row_mask:0xf bank_mask:0xf
	v_fmac_f32_dpp v124, v112, v42 row_newbcast:10 row_mask:0xf bank_mask:0xf
	v_fmac_f32_dpp v125, v112, v43 row_newbcast:11 row_mask:0xf bank_mask:0xf
	v_fmac_f32_dpp v124, v112, v44 row_newbcast:12 row_mask:0xf bank_mask:0xf
	v_fmac_f32_dpp v125, v112, v45 row_newbcast:13 row_mask:0xf bank_mask:0xf
	v_fmac_f32_dpp v124, v112, v46 row_newbcast:14 row_mask:0xf bank_mask:0xf
	v_fmac_f32_dpp v125, v112, v47 row_newbcast:15 row_mask:0xf bank_mask:0xf
	v_fmac_f32_dpp v124, v113, v48 row_newbcast:0 row_mask:0xf bank_mask:0xf
	v_fmac_f32_dpp v125, v113, v49 row_newbcast:1 row_mask:0xf bank_mask:0xf
	v_fmac_f32_dpp v124, v113, v50 row_newbcast:2 row_mask:0xf bank_mask:0xf
	v_fmac_f32_dpp v125, v113, v51 row_newbcast:3 row_mask:0xf bank_mask:0xf
	v_mfma_f32_32x32x2_f32 v[80:95], v105, v108, v[48:63]
	v_fmac_f32_dpp v124, v113, v52 row_newbcast:4 row_mask:0xf bank_mask:0xf
	v_fmac_f32_dpp v125, v113, v53 row_newbcast:5 row_mask:0xf bank_mask:0xf
	v_fmac_f32_dpp v124, v113, v54 row_newbcast:6 row_mask:0xf bank_mask:0xf
	v_fmac_f32_dpp v125, v113, v55 row_newbcast:7 row_mask:0xf bank_mask:0xf
	v_fmac_f32_dpp v124, v113, v56 row_newbcast:8 row_mask:0xf bank_mask:0xf
	v_fmac_f32_dpp v125, v113, v57 row_newbcast:9 row_mask:0xf bank_mask:0xf
	v_fmac_f32_dpp v124, v113, v58 row_newbcast:10 row_mask:0xf bank_mask:0xf
	v_fmac_f32_dpp v125, v113, v59 row_newbcast:11 row_mask:0xf bank_mask:0xf
	v_fmac_f32_dpp v124, v113, v60 row_newbcast:12 row_mask:0xf bank_mask:0xf
	v_fmac_f32_dpp v125, v113, v61 row_newbcast:13 row_mask:0xf bank_mask:0xf
	v_fmac_f32_dpp v124, v113, v62 row_newbcast:14 row_mask:0xf bank_mask:0xf
	v_fmac_f32_dpp v125, v113, v63 row_newbcast:15 row_mask:0xf bank_mask:0xf
	v_add_f32_e32 v131, v124, v125
	s_nop 1
	v_permlane32_swap_b32 v130, v131
	v_add_f32_e32 v133, v130, v131
	v_cvt_pk_bf16_f32 v133, v133, v133
	global_store_short v13, v133, s[16:17]
	s_add_u32 s16, s16, s20
	s_addc_u32 s17, s17, s21
	s_waitcnt lgkmcnt(0)
	v_mul_f32_dpp v120, v102, v64 row_newbcast:0 row_mask:0xf bank_mask:0xf
	v_mul_f32_dpp v121, v102, v65 row_newbcast:1 row_mask:0xf bank_mask:0xf
	v_fmac_f32_dpp v120, v102, v66 row_newbcast:2 row_mask:0xf bank_mask:0xf
	v_fmac_f32_dpp v121, v102, v67 row_newbcast:3 row_mask:0xf bank_mask:0xf
	v_fmac_f32_dpp v120, v102, v68 row_newbcast:4 row_mask:0xf bank_mask:0xf
	v_fmac_f32_dpp v121, v102, v69 row_newbcast:5 row_mask:0xf bank_mask:0xf
	v_fmac_f32_dpp v120, v102, v70 row_newbcast:6 row_mask:0xf bank_mask:0xf
	v_fmac_f32_dpp v121, v102, v71 row_newbcast:7 row_mask:0xf bank_mask:0xf
	v_fmac_f32_dpp v120, v102, v72 row_newbcast:8 row_mask:0xf bank_mask:0xf
	v_fmac_f32_dpp v121, v102, v73 row_newbcast:9 row_mask:0xf bank_mask:0xf
	v_fmac_f32_dpp v120, v102, v74 row_newbcast:10 row_mask:0xf bank_mask:0xf
	v_fmac_f32_dpp v121, v102, v75 row_newbcast:11 row_mask:0xf bank_mask:0xf
	v_fmac_f32_dpp v120, v102, v76 row_newbcast:12 row_mask:0xf bank_mask:0xf
	v_fmac_f32_dpp v121, v102, v77 row_newbcast:13 row_mask:0xf bank_mask:0xf
	v_fmac_f32_dpp v120, v102, v78 row_newbcast:14 row_mask:0xf bank_mask:0xf
	v_fmac_f32_dpp v121, v102, v79 row_newbcast:15 row_mask:0xf bank_mask:0xf
	v_fmac_f32_dpp v120, v103, v80 row_newbcast:0 row_mask:0xf bank_mask:0xf
	v_fmac_f32_dpp v121, v103, v81 row_newbcast:1 row_mask:0xf bank_mask:0xf
	v_fmac_f32_dpp v120, v103, v82 row_newbcast:2 row_mask:0xf bank_mask:0xf
	v_fmac_f32_dpp v121, v103, v83 row_newbcast:3 row_mask:0xf bank_mask:0xf
	v_fmac_f32_dpp v120, v103, v84 row_newbcast:4 row_mask:0xf bank_mask:0xf
	v_fmac_f32_dpp v121, v103, v85 row_newbcast:5 row_mask:0xf bank_mask:0xf
	v_fmac_f32_dpp v120, v103, v86 row_newbcast:6 row_mask:0xf bank_mask:0xf
	v_fmac_f32_dpp v121, v103, v87 row_newbcast:7 row_mask:0xf bank_mask:0xf
	v_fmac_f32_dpp v120, v103, v88 row_newbcast:8 row_mask:0xf bank_mask:0xf
	v_fmac_f32_dpp v121, v103, v89 row_newbcast:9 row_mask:0xf bank_mask:0xf
	v_fmac_f32_dpp v120, v103, v90 row_newbcast:10 row_mask:0xf bank_mask:0xf
	v_fmac_f32_dpp v121, v103, v91 row_newbcast:11 row_mask:0xf bank_mask:0xf
	v_fmac_f32_dpp v120, v103, v92 row_newbcast:12 row_mask:0xf bank_mask:0xf
	v_fmac_f32_dpp v121, v103, v93 row_newbcast:13 row_mask:0xf bank_mask:0xf
	v_fmac_f32_dpp v120, v103, v94 row_newbcast:14 row_mask:0xf bank_mask:0xf
	v_fmac_f32_dpp v121, v103, v95 row_newbcast:15 row_mask:0xf bank_mask:0xf
	v_add_f32_e32 v128, v120, v121
	v_mul_f32_dpp v124, v114, v64 row_newbcast:0 row_mask:0xf bank_mask:0xf
	v_mul_f32_dpp v125, v114, v65 row_newbcast:1 row_mask:0xf bank_mask:0xf
	v_permlane32_swap_b32 v129, v128
	v_fmac_f32_dpp v124, v114, v66 row_newbcast:2 row_mask:0xf bank_mask:0xf
	v_fmac_f32_dpp v125, v114, v67 row_newbcast:3 row_mask:0xf bank_mask:0xf
	v_add_f32_dpp v109, -v129, -v128 quad_perm:[0,1,2,3] row_mask:0xc bank_mask:0xf
	v_fmac_f32_dpp v124, v114, v68 row_newbcast:4 row_mask:0xf bank_mask:0xf
	v_fmac_f32_dpp v125, v114, v69 row_newbcast:5 row_mask:0xf bank_mask:0xf
	v_mfma_f32_32x32x2_f32 v[32:47], v106, v109, v[64:79]
	v_fmac_f32_dpp v124, v114, v70 row_newbcast:6 row_mask:0xf bank_mask:0xf
	v_fmac_f32_dpp v125, v114, v71 row_newbcast:7 row_mask:0xf bank_mask:0xf
	v_fmac_f32_dpp v124, v114, v72 row_newbcast:8 row_mask:0xf bank_mask:0xf
	v_fmac_f32_dpp v125, v114, v73 row_newbcast:9 row_mask:0xf bank_mask:0xf
	v_fmac_f32_dpp v124, v114, v74 row_newbcast:10 row_mask:0xf bank_mask:0xf
	v_fmac_f32_dpp v125, v114, v75 row_newbcast:11 row_mask:0xf bank_mask:0xf
	v_fmac_f32_dpp v124, v114, v76 row_newbcast:12 row_mask:0xf bank_mask:0xf
	v_fmac_f32_dpp v125, v114, v77 row_newbcast:13 row_mask:0xf bank_mask:0xf
	v_fmac_f32_dpp v124, v114, v78 row_newbcast:14 row_mask:0xf bank_mask:0xf
	v_fmac_f32_dpp v125, v114, v79 row_newbcast:15 row_mask:0xf bank_mask:0xf
	v_fmac_f32_dpp v124, v115, v80 row_newbcast:0 row_mask:0xf bank_mask:0xf
	v_fmac_f32_dpp v125, v115, v81 row_newbcast:1 row_mask:0xf bank_mask:0xf
	v_fmac_f32_dpp v124, v115, v82 row_newbcast:2 row_mask:0xf bank_mask:0xf
; __device__ void scan_chain(PRef p, int l, int chain, ScanSm* sm) {
;     ...
; #pragma unroll 1
;     for (int c = 0; c < 144; c++) {
;       __syncthreads();
;       const ScanRec* rc0 = &sm->rec[c & 1][0];
;       LDSET(A, rc0)
; #pragma unroll 1
;       for (int i2 = 0; i2 < 8; i2++) {
;         const ScanRec* rcA = rc0 + 2 * i2;
;         const ScanRec* rcC = (i2 < 7) ? rcA + 2 : rcA + 1;
;         LDSET(B, rcA + 1)
;         SCAN_STEP(A, c * 16 + 2 * i2)
;         LDSET(A, rcC)
;         SCAN_STEP(B, c * 16 + 2 * i2 + 1)
;       }
;     }
	v_fmac_f32_dpp v125, v115, v83 row_newbcast:3 row_mask:0xf bank_mask:0xf
	v_mfma_f32_32x32x2_f32 v[48:63], v107, v109, v[80:95]
	v_fmac_f32_dpp v124, v115, v84 row_newbcast:4 row_mask:0xf bank_mask:0xf
	v_fmac_f32_dpp v125, v115, v85 row_newbcast:5 row_mask:0xf bank_mask:0xf
	v_fmac_f32_dpp v124, v115, v86 row_newbcast:6 row_mask:0xf bank_mask:0xf
	v_fmac_f32_dpp v125, v115, v87 row_newbcast:7 row_mask:0xf bank_mask:0xf
	v_fmac_f32_dpp v124, v115, v88 row_newbcast:8 row_mask:0xf bank_mask:0xf
	v_fmac_f32_dpp v125, v115, v89 row_newbcast:9 row_mask:0xf bank_mask:0xf
	v_fmac_f32_dpp v124, v115, v90 row_newbcast:10 row_mask:0xf bank_mask:0xf
	v_fmac_f32_dpp v125, v115, v91 row_newbcast:11 row_mask:0xf bank_mask:0xf
	v_fmac_f32_dpp v124, v115, v92 row_newbcast:12 row_mask:0xf bank_mask:0xf
	v_fmac_f32_dpp v125, v115, v93 row_newbcast:13 row_mask:0xf bank_mask:0xf
	v_fmac_f32_dpp v124, v115, v94 row_newbcast:14 row_mask:0xf bank_mask:0xf
	v_fmac_f32_dpp v125, v115, v95 row_newbcast:15 row_mask:0xf bank_mask:0xf
	v_add_f32_e32 v130, v124, v125
	v_mul_f32_dpp v124, v116, v32 row_newbcast:0 row_mask:0xf bank_mask:0xf
	v_mul_f32_dpp v125, v116, v33 row_newbcast:1 row_mask:0xf bank_mask:0xf
	v_fmac_f32_dpp v124, v116, v34 row_newbcast:2 row_mask:0xf bank_mask:0xf
	v_fmac_f32_dpp v125, v116, v35 row_newbcast:3 row_mask:0xf bank_mask:0xf
	v_fmac_f32_dpp v124, v116, v36 row_newbcast:4 row_mask:0xf bank_mask:0xf
	v_fmac_f32_dpp v125, v116, v37 row_newbcast:5 row_mask:0xf bank_mask:0xf
	v_fmac_f32_dpp v124, v116, v38 row_newbcast:6 row_mask:0xf bank_mask:0xf
	v_fmac_f32_dpp v125, v116, v39 row_newbcast:7 row_mask:0xf bank_mask:0xf
	v_fmac_f32_dpp v124, v116, v40 row_newbcast:8 row_mask:0xf bank_mask:0xf
	v_fmac_f32_dpp v125, v116, v41 row_newbcast:9 row_mask:0xf bank_mask:0xf
	v_fmac_f32_dpp v124, v116, v42 row_newbcast:10 row_mask:0xf bank_mask:0xf
	v_fmac_f32_dpp v125, v116, v43 row_newbcast:11 row_mask:0xf bank_mask:0xf
	v_fmac_f32_dpp v124, v116, v44 row_newbcast:12 row_mask:0xf bank_mask:0xf
	v_fmac_f32_dpp v125, v116, v45 row_newbcast:13 row_mask:0xf bank_mask:0xf
	v_fmac_f32_dpp v124, v116, v46 row_newbcast:14 row_mask:0xf bank_mask:0xf
	v_fmac_f32_dpp v125, v116, v47 row_newbcast:15 row_mask:0xf bank_mask:0xf
	v_fmac_f32_dpp v124, v117, v48 row_newbcast:0 row_mask:0xf bank_mask:0xf
	v_fmac_f32_dpp v125, v117, v49 row_newbcast:1 row_mask:0xf bank_mask:0xf
	v_fmac_f32_dpp v124, v117, v50 row_newbcast:2 row_mask:0xf bank_mask:0xf
	v_fmac_f32_dpp v125, v117, v51 row_newbcast:3 row_mask:0xf bank_mask:0xf
	v_fmac_f32_dpp v124, v117, v52 row_newbcast:4 row_mask:0xf bank_mask:0xf
	v_fmac_f32_dpp v125, v117, v53 row_newbcast:5 row_mask:0xf bank_mask:0xf
	v_fmac_f32_dpp v124, v117, v54 row_newbcast:6 row_mask:0xf bank_mask:0xf
	v_fmac_f32_dpp v125, v117, v55 row_newbcast:7 row_mask:0xf bank_mask:0xf
	v_fmac_f32_dpp v124, v117, v56 row_newbcast:8 row_mask:0xf bank_mask:0xf
	v_fmac_f32_dpp v125, v117, v57 row_newbcast:9 row_mask:0xf bank_mask:0xf
	v_fmac_f32_dpp v124, v117, v58 row_newbcast:10 row_mask:0xf bank_mask:0xf
	v_fmac_f32_dpp v125, v117, v59 row_newbcast:11 row_mask:0xf bank_mask:0xf
	v_fmac_f32_dpp v124, v117, v60 row_newbcast:12 row_mask:0xf bank_mask:0xf
	v_fmac_f32_dpp v125, v117, v61 row_newbcast:13 row_mask:0xf bank_mask:0xf
	v_fmac_f32_dpp v124, v117, v62 row_newbcast:14 row_mask:0xf bank_mask:0xf
	v_fmac_f32_dpp v125, v117, v63 row_newbcast:15 row_mask:0xf bank_mask:0xf
	v_add_f32_e32 v131, v124, v125
	s_nop 1
	v_permlane32_swap_b32 v130, v131
	v_add_f32_e32 v133, v130, v131
	v_cvt_pk_bf16_f32 v133, v133, v133
	global_store_short v13, v133, s[16:17]
	s_add_u32 s16, s16, s20
	s_addc_u32 s17, s17, s21
	v_mul_f32_dpp v32, v118, v32 row_newbcast:0 row_mask:0xf bank_mask:0xf
	v_mul_f32_dpp v33, v118, v33 row_newbcast:1 row_mask:0xf bank_mask:0xf
	v_mul_f32_dpp v34, v118, v34 row_newbcast:2 row_mask:0xf bank_mask:0xf
	v_mul_f32_dpp v35, v118, v35 row_newbcast:3 row_mask:0xf bank_mask:0xf
	v_mul_f32_dpp v36, v118, v36 row_newbcast:4 row_mask:0xf bank_mask:0xf
	v_mul_f32_dpp v37, v118, v37 row_newbcast:5 row_mask:0xf bank_mask:0xf
	v_mul_f32_dpp v38, v118, v38 row_newbcast:6 row_mask:0xf bank_mask:0xf
	v_mul_f32_dpp v39, v118, v39 row_newbcast:7 row_mask:0xf bank_mask:0xf
	v_mul_f32_dpp v40, v118, v40 row_newbcast:8 row_mask:0xf bank_mask:0xf
	v_mul_f32_dpp v41, v118, v41 row_newbcast:9 row_mask:0xf bank_mask:0xf
	v_mul_f32_dpp v42, v118, v42 row_newbcast:10 row_mask:0xf bank_mask:0xf
	v_mul_f32_dpp v43, v118, v43 row_newbcast:11 row_mask:0xf bank_mask:0xf
	v_mul_f32_dpp v44, v118, v44 row_newbcast:12 row_mask:0xf bank_mask:0xf
	v_mul_f32_dpp v45, v118, v45 row_newbcast:13 row_mask:0xf bank_mask:0xf
	v_mul_f32_dpp v46, v118, v46 row_newbcast:14 row_mask:0xf bank_mask:0xf
	v_mul_f32_dpp v47, v118, v47 row_newbcast:15 row_mask:0xf bank_mask:0xf
	v_mul_f32_dpp v48, v119, v48 row_newbcast:0 row_mask:0xf bank_mask:0xf
	v_mul_f32_dpp v49, v119, v49 row_newbcast:1 row_mask:0xf bank_mask:0xf
	v_mul_f32_dpp v50, v119, v50 row_newbcast:2 row_mask:0xf bank_mask:0xf
	v_mul_f32_dpp v51, v119, v51 row_newbcast:3 row_mask:0xf bank_mask:0xf
	v_mul_f32_dpp v52, v119, v52 row_newbcast:4 row_mask:0xf bank_mask:0xf
	v_mul_f32_dpp v53, v119, v53 row_newbcast:5 row_mask:0xf bank_mask:0xf
	v_mul_f32_dpp v54, v119, v54 row_newbcast:6 row_mask:0xf bank_mask:0xf
	v_mul_f32_dpp v55, v119, v55 row_newbcast:7 row_mask:0xf bank_mask:0xf
	v_mul_f32_dpp v56, v119, v56 row_newbcast:8 row_mask:0xf bank_mask:0xf
	v_mul_f32_dpp v57, v119, v57 row_newbcast:9 row_mask:0xf bank_mask:0xf
	v_mul_f32_dpp v58, v119, v58 row_newbcast:10 row_mask:0xf bank_mask:0xf
	v_mul_f32_dpp v59, v119, v59 row_newbcast:11 row_mask:0xf bank_mask:0xf
	v_mul_f32_dpp v60, v119, v60 row_newbcast:12 row_mask:0xf bank_mask:0xf
	v_mul_f32_dpp v61, v119, v61 row_newbcast:13 row_mask:0xf bank_mask:0xf
	v_mul_f32_dpp v62, v119, v62 row_newbcast:14 row_mask:0xf bank_mask:0xf
	v_mul_f32_dpp v63, v119, v63 row_newbcast:15 row_mask:0xf bank_mask:0xf
	s_add_i32 s15, s15, 1
	s_cmpk_lg_i32 s15, 0x90
	s_cbranch_scc1 .Lscan_chunk
	s_branch .LBB0_564
